# GEMM K-loops: also removed the redundant s_waitcnt lgkmcnt(0) at the head of each MFMA segment (already drained before the barrier)
# speedup vs baseline: 1.0180x; 1.0180x over previous
; #define PG8_STAGE(bufoff, gbase, voff) do { _Pragma("unroll") for (int _i = 0; _i < 2; ++_i) \
;         __builtin_amdgcn_global_load_lds((const unsigned*)((const char*)(gbase) + (voff)[_i]), (PG8_LAS unsigned*)(lds + (bufoff) + ldsw + _i * 8192), 16, 0, 0); } while (0)
; #define PG8_LDA(dst, b, h) do { _Pragma("unroll") for (int m = 0; m < 4; ++m) _Pragma("unroll") for (int k = 0; k < 2; ++k) dst[m][k] = *(const PG8_LAS bf16x8*)(lds + PG8_SA(b, h) + aoff + m * 2048 + k * 1024); } while (0)
; #define PG8_MMA(ai, bj, At, Bt) do { __builtin_amdgcn_s_setprio(1); _Pragma("unroll") for (int m = 0; m < 4; ++m) _Pragma("unroll") for (int n = 0; n < 2; ++n) _Pragma("unroll") for (int k = 0; k < 2; ++k) \
;         acc[ai][bj][m][n] = __builtin_amdgcn_mfma_f32_16x16x32_bf16(Bt[n][k], At[m][k], acc[ai][bj][m][n], 0, 0, 0); __builtin_amdgcn_s_setprio(0); } while (0)
; #define PG8_WAIT_V(n) asm volatile("s_waitcnt vmcnt(" #n ")" ::: "memory")
; #define PG8_WAIT_L(n) asm volatile("s_waitcnt lgkmcnt(" #n ")" ::: "memory")
; #define PG8_BAR __builtin_amdgcn_s_barrier()
; #define PG8_SCHED __builtin_amdgcn_sched_barrier(0)
; template <class Epi, class Sched, bool ALIGN_EPI = false, bool SP2 = false>
; __device__ __forceinline__ void gemm_phase(PG8_LAS unsigned char* lds, const Gemm g, const Sched& S, const Epi& E) {
;     ...
;             PG8_WAIT_V(8); PG8_WAIT_L(0); PG8_BAR; PG8_MMA(0, 0, At, B0); PG8_MMA(0, 1, At, B1); PG8_BAR; PG8_SCHED;
;             PG8_LDA(At, 0, 1); PG8_STAGE(PG8_SB(0, 0), b2, voffB); PG8_STAGE(PG8_SB(0, 1), b2 + hstep, voffB); PG8_STAGE(PG8_SA(0, 0), a2, voffA);
;             PG8_WAIT_V(8); PG8_WAIT_L(0); PG8_BAR; PG8_MMA(1, 0, At, B0); PG8_MMA(1, 1, At, B1); PG8_BAR; PG8_SCHED;
.Lodin_noz:
	s_waitcnt vmcnt(8)
	s_waitcnt lgkmcnt(0)
	s_barrier
	s_setprio 1
	v_mfma_f32_16x16x32_bf16 v[70:73], v[130:133], v[188:191], v[70:73]
	v_mfma_f32_16x16x32_bf16 v[66:69], v[158:161], v[188:191], v[66:69]
	v_mfma_f32_16x16x32_bf16 v[62:65], v[130:133], v[196:199], v[62:65]
	v_mfma_f32_16x16x32_bf16 v[58:61], v[158:161], v[196:199], v[58:61]
	v_mfma_f32_16x16x32_bf16 v[54:57], v[130:133], v[204:207], v[54:57]
	v_mfma_f32_16x16x32_bf16 v[50:53], v[158:161], v[204:207], v[50:53]
	v_mfma_f32_16x16x32_bf16 v[46:49], v[130:133], v[212:215], v[46:49]
	v_mfma_f32_16x16x32_bf16 v[42:45], v[158:161], v[212:215], v[42:45]
	v_mfma_f32_16x16x32_bf16 v[70:73], v[154:157], v[192:195], v[70:73]
	v_mfma_f32_16x16x32_bf16 v[66:69], v[162:165], v[192:195], v[66:69]
	v_mfma_f32_16x16x32_bf16 v[62:65], v[154:157], v[200:203], v[62:65]
	v_mfma_f32_16x16x32_bf16 v[58:61], v[162:165], v[200:203], v[58:61]
	v_mfma_f32_16x16x32_bf16 v[54:57], v[154:157], v[208:211], v[54:57]
	v_mfma_f32_16x16x32_bf16 v[50:53], v[162:165], v[208:211], v[50:53]
	v_mfma_f32_16x16x32_bf16 v[46:49], v[154:157], v[216:219], v[46:49]
	v_mfma_f32_16x16x32_bf16 v[42:45], v[162:165], v[216:219], v[42:45]
	v_mfma_f32_16x16x32_bf16 v[126:129], v[166:169], v[188:191], v[126:129]
	v_mfma_f32_16x16x32_bf16 v[122:125], v[180:183], v[188:191], v[122:125]
	v_mfma_f32_16x16x32_bf16 v[118:121], v[166:169], v[196:199], v[118:121]
	v_mfma_f32_16x16x32_bf16 v[114:117], v[180:183], v[196:199], v[114:117]
	v_mfma_f32_16x16x32_bf16 v[110:113], v[166:169], v[204:207], v[110:113]
	v_mfma_f32_16x16x32_bf16 v[106:109], v[180:183], v[204:207], v[106:109]
	v_mfma_f32_16x16x32_bf16 v[102:105], v[166:169], v[212:215], v[102:105]
	v_mfma_f32_16x16x32_bf16 v[98:101], v[180:183], v[212:215], v[98:101]
	v_mfma_f32_16x16x32_bf16 v[126:129], v[170:173], v[192:195], v[126:129]
	v_mfma_f32_16x16x32_bf16 v[122:125], v[184:187], v[192:195], v[122:125]
	v_mfma_f32_16x16x32_bf16 v[118:121], v[170:173], v[200:203], v[118:121]
	v_mfma_f32_16x16x32_bf16 v[114:117], v[184:187], v[200:203], v[114:117]
	v_mfma_f32_16x16x32_bf16 v[110:113], v[170:173], v[208:211], v[110:113]
	v_mfma_f32_16x16x32_bf16 v[106:109], v[184:187], v[208:211], v[106:109]
	v_mfma_f32_16x16x32_bf16 v[102:105], v[170:173], v[216:219], v[102:105]
	v_mfma_f32_16x16x32_bf16 v[98:101], v[184:187], v[216:219], v[98:101]
	s_setprio 0
	s_barrier
	s_add_i32 s55, s55, s39
	v_lshl_add_u64 v[146:147], s[30:31], 0, v[138:139]
	s_mov_b32 m0, s55
	ds_read_b128 v[188:191], v153 offset:16384
	ds_read_b128 v[192:195], v153 offset:17408
	ds_read_b128 v[196:199], v153 offset:18432
	ds_read_b128 v[200:203], v153 offset:19456
	ds_read_b128 v[204:207], v153 offset:20480
	ds_read_b128 v[208:211], v153 offset:21504
	ds_read_b128 v[212:215], v153 offset:22528
	ds_read_b128 v[216:219], v153 offset:23552
	global_load_lds_dwordx4 v[146:147], off
	s_add_i32 m0, s55, 0x2000
	s_add_u32 s56, s30, 0x40000
	v_lshl_add_u64 v[220:221], s[30:31], 0, v[134:135]
	s_addc_u32 s57, s31, 0
	s_add_i32 s55, s58, s39
	global_load_lds_dwordx4 v[220:221], off
	v_lshl_add_u64 v[222:223], s[56:57], 0, v[138:139]
	s_mov_b32 m0, s55
	v_lshl_add_u64 v[228:229], s[34:35], 0, v[136:137]
	global_load_lds_dwordx4 v[222:223], off
	v_lshl_add_u64 v[222:223], s[56:57], 0, v[134:135]
	s_add_i32 m0, s55, 0x2000
	s_nop 0
	global_load_lds_dwordx4 v[222:223], off
	v_lshl_add_u64 v[222:223], s[34:35], 0, v[140:141]
	s_mov_b32 m0, s40
	s_nop 0
	global_load_lds_dwordx4 v[222:223], off
	s_mov_b32 m0, s41
	s_nop 0
	global_load_lds_dwordx4 v[228:229], off
	s_waitcnt vmcnt(8)
	s_waitcnt lgkmcnt(0)
	s_barrier
	s_setprio 1
	v_mfma_f32_16x16x32_bf16 v[30:33], v[130:133], v[188:191], v[30:33]
	v_mfma_f32_16x16x32_bf16 v[26:29], v[158:161], v[188:191], v[26:29]
	v_mfma_f32_16x16x32_bf16 v[22:25], v[130:133], v[196:199], v[22:25]
	v_mfma_f32_16x16x32_bf16 v[18:21], v[158:161], v[196:199], v[18:21]
	v_mfma_f32_16x16x32_bf16 v[14:17], v[130:133], v[204:207], v[14:17]
	v_mfma_f32_16x16x32_bf16 v[10:13], v[158:161], v[204:207], v[10:13]
	v_mfma_f32_16x16x32_bf16 v[6:9], v[130:133], v[212:215], v[6:9]
	v_mfma_f32_16x16x32_bf16 v[2:5], v[158:161], v[212:215], v[2:5]
	v_mfma_f32_16x16x32_bf16 v[30:33], v[154:157], v[192:195], v[30:33]
	v_mfma_f32_16x16x32_bf16 v[26:29], v[162:165], v[192:195], v[26:29]
	v_mfma_f32_16x16x32_bf16 v[22:25], v[154:157], v[200:203], v[22:25]
	v_mfma_f32_16x16x32_bf16 v[18:21], v[162:165], v[200:203], v[18:21]
	v_mfma_f32_16x16x32_bf16 v[14:17], v[154:157], v[208:211], v[14:17]
	v_mfma_f32_16x16x32_bf16 v[10:13], v[162:165], v[208:211], v[10:13]
	v_mfma_f32_16x16x32_bf16 v[6:9], v[154:157], v[216:219], v[6:9]
	v_mfma_f32_16x16x32_bf16 v[2:5], v[162:165], v[216:219], v[2:5]
	v_mfma_f32_16x16x32_bf16 v[94:97], v[166:169], v[188:191], v[94:97]
	v_mfma_f32_16x16x32_bf16 v[90:93], v[180:183], v[188:191], v[90:93]
	v_mfma_f32_16x16x32_bf16 v[86:89], v[166:169], v[196:199], v[86:89]
	v_mfma_f32_16x16x32_bf16 v[82:85], v[180:183], v[196:199], v[82:85]
	v_mfma_f32_16x16x32_bf16 v[78:81], v[166:169], v[204:207], v[78:81]
	v_mfma_f32_16x16x32_bf16 v[74:77], v[180:183], v[204:207], v[74:77]
	v_mfma_f32_16x16x32_bf16 v[38:41], v[166:169], v[212:215], v[38:41]
	v_mfma_f32_16x16x32_bf16 v[34:37], v[180:183], v[212:215], v[34:37]
	v_mfma_f32_16x16x32_bf16 v[94:97], v[170:173], v[192:195], v[94:97]
	v_mfma_f32_16x16x32_bf16 v[90:93], v[184:187], v[192:195], v[90:93]
	v_mfma_f32_16x16x32_bf16 v[86:89], v[170:173], v[200:203], v[86:89]
	v_mfma_f32_16x16x32_bf16 v[82:85], v[184:187], v[200:203], v[82:85]
	v_mfma_f32_16x16x32_bf16 v[78:81], v[170:173], v[208:211], v[78:81]
	v_mfma_f32_16x16x32_bf16 v[74:77], v[184:187], v[208:211], v[74:77]
	v_mfma_f32_16x16x32_bf16 v[38:41], v[170:173], v[216:219], v[38:41]
	v_mfma_f32_16x16x32_bf16 v[34:37], v[184:187], v[216:219], v[34:37]
	s_setprio 0
	s_barrier
; #define PG8_STAGE(bufoff, gbase, voff) do { _Pragma("unroll") for (int _i = 0; _i < 2; ++_i) \
;         __builtin_amdgcn_global_load_lds((const unsigned*)((const char*)(gbase) + (voff)[_i]), (PG8_LAS unsigned*)(lds + (bufoff) + ldsw + _i * 8192), 16, 0, 0); } while (0)
; #define PG8_LDA(dst, b, h) do { _Pragma("unroll") for (int m = 0; m < 4; ++m) _Pragma("unroll") for (int k = 0; k < 2; ++k) dst[m][k] = *(const PG8_LAS bf16x8*)(lds + PG8_SA(b, h) + aoff + m * 2048 + k * 1024); } while (0)
; #define PG8_LDB(dst, b, h) do { _Pragma("unroll") for (int n = 0; n < 2; ++n) _Pragma("unroll") for (int k = 0; k < 2; ++k) dst[n][k] = *(const PG8_LAS bf16x8*)(lds + PG8_SB(b, h) + boff + n * 2048 + k * 1024); } while (0)
; #define PG8_MMA(ai, bj, At, Bt) do { __builtin_amdgcn_s_setprio(1); _Pragma("unroll") for (int m = 0; m < 4; ++m) _Pragma("unroll") for (int n = 0; n < 2; ++n) _Pragma("unroll") for (int k = 0; k < 2; ++k) \
;         acc[ai][bj][m][n] = __builtin_amdgcn_mfma_f32_16x16x32_bf16(Bt[n][k], At[m][k], acc[ai][bj][m][n], 0, 0, 0); __builtin_amdgcn_s_setprio(0); } while (0)
; #define PG8_WAIT_V(n) asm volatile("s_waitcnt vmcnt(" #n ")" ::: "memory")
; #define PG8_WAIT_L(n) asm volatile("s_waitcnt lgkmcnt(" #n ")" ::: "memory")
; #define PG8_BAR __builtin_amdgcn_s_barrier()
; #define PG8_SCHED __builtin_amdgcn_sched_barrier(0)
; template <class Epi, class Sched, bool ALIGN_EPI = false, bool SP2 = false>
; __device__ __forceinline__ void gemm_phase(PG8_LAS unsigned char* lds, const Gemm g, const Sched& S, const Epi& E) {
;     ...
;             PG8_LDB(B0, 1, 0); PG8_LDB(B1, 1, 1); PG8_SCHED; PG8_LDA(At, 1, 0); PG8_STAGE(PG8_SA(0, 1), a2 + hstep, voffA);
;             PG8_WAIT_V(8); PG8_WAIT_L(0); PG8_BAR; PG8_MMA(0, 0, At, B0); PG8_MMA(0, 1, At, B1); PG8_BAR; PG8_SCHED;
	s_add_i32 s55, 0, 0x18000
	v_add_u32_e32 v148, s55, v151
	s_add_i32 s56, 0, 0x1c000
	ds_read_b128 v[130:133], v148
	ds_read_b128 v[154:157], v148 offset:1024
	ds_read_b128 v[158:161], v148 offset:2048
	ds_read_b128 v[162:165], v148 offset:3072
	v_add_u32_e32 v148, s56, v151
	ds_read_b128 v[166:169], v148
	ds_read_b128 v[170:173], v148 offset:1024
	ds_read_b128 v[180:183], v148 offset:2048
	ds_read_b128 v[184:187], v148 offset:3072
	s_add_u32 s34, s34, 0x40000
	s_addc_u32 s35, s35, 0
	s_mov_b32 m0, s42
	v_lshl_add_u64 v[230:231], s[34:35], 0, v[140:141]
	ds_read_b128 v[188:191], v153 offset:32768
	ds_read_b128 v[192:195], v153 offset:33792
	ds_read_b128 v[196:199], v153 offset:34816
	ds_read_b128 v[200:203], v153 offset:35840
	ds_read_b128 v[204:207], v153 offset:36864
	ds_read_b128 v[208:211], v153 offset:37888
	ds_read_b128 v[212:215], v153 offset:38912
	ds_read_b128 v[216:219], v153 offset:39936
	global_load_lds_dwordx4 v[230:231], off
	v_lshl_add_u64 v[230:231], s[34:35], 0, v[136:137]
	s_mov_b32 m0, s43
	s_nop 0
	global_load_lds_dwordx4 v[230:231], off
	s_waitcnt vmcnt(8)
	s_waitcnt lgkmcnt(0)
	s_barrier
	s_setprio 1
	v_mfma_f32_16x16x32_bf16 v[70:73], v[130:133], v[188:191], v[70:73]
	v_mfma_f32_16x16x32_bf16 v[66:69], v[158:161], v[188:191], v[66:69]
	v_mfma_f32_16x16x32_bf16 v[62:65], v[130:133], v[196:199], v[62:65]
	v_mfma_f32_16x16x32_bf16 v[58:61], v[158:161], v[196:199], v[58:61]
	v_mfma_f32_16x16x32_bf16 v[54:57], v[130:133], v[204:207], v[54:57]
	v_mfma_f32_16x16x32_bf16 v[50:53], v[158:161], v[204:207], v[50:53]
	v_mfma_f32_16x16x32_bf16 v[46:49], v[130:133], v[212:215], v[46:49]
	v_mfma_f32_16x16x32_bf16 v[42:45], v[158:161], v[212:215], v[42:45]
	v_mfma_f32_16x16x32_bf16 v[70:73], v[154:157], v[192:195], v[70:73]
	v_mfma_f32_16x16x32_bf16 v[66:69], v[162:165], v[192:195], v[66:69]
	v_mfma_f32_16x16x32_bf16 v[62:65], v[154:157], v[200:203], v[62:65]
	v_mfma_f32_16x16x32_bf16 v[58:61], v[162:165], v[200:203], v[58:61]
	v_mfma_f32_16x16x32_bf16 v[54:57], v[154:157], v[208:211], v[54:57]
	v_mfma_f32_16x16x32_bf16 v[50:53], v[162:165], v[208:211], v[50:53]
	v_mfma_f32_16x16x32_bf16 v[46:49], v[154:157], v[216:219], v[46:49]
	v_mfma_f32_16x16x32_bf16 v[42:45], v[162:165], v[216:219], v[42:45]
	v_mfma_f32_16x16x32_bf16 v[126:129], v[166:169], v[188:191], v[126:129]
	v_mfma_f32_16x16x32_bf16 v[122:125], v[180:183], v[188:191], v[122:125]
	v_mfma_f32_16x16x32_bf16 v[118:121], v[166:169], v[196:199], v[118:121]
	v_mfma_f32_16x16x32_bf16 v[114:117], v[180:183], v[196:199], v[114:117]
	v_mfma_f32_16x16x32_bf16 v[110:113], v[166:169], v[204:207], v[110:113]
	v_mfma_f32_16x16x32_bf16 v[106:109], v[180:183], v[204:207], v[106:109]
	v_mfma_f32_16x16x32_bf16 v[102:105], v[166:169], v[212:215], v[102:105]
	v_mfma_f32_16x16x32_bf16 v[98:101], v[180:183], v[212:215], v[98:101]
	v_mfma_f32_16x16x32_bf16 v[126:129], v[170:173], v[192:195], v[126:129]
	v_mfma_f32_16x16x32_bf16 v[122:125], v[184:187], v[192:195], v[122:125]
	v_mfma_f32_16x16x32_bf16 v[118:121], v[170:173], v[200:203], v[118:121]
	v_mfma_f32_16x16x32_bf16 v[114:117], v[184:187], v[200:203], v[114:117]
	v_mfma_f32_16x16x32_bf16 v[110:113], v[170:173], v[208:211], v[110:113]
	v_mfma_f32_16x16x32_bf16 v[106:109], v[184:187], v[208:211], v[106:109]
	v_mfma_f32_16x16x32_bf16 v[102:105], v[170:173], v[216:219], v[102:105]
	v_mfma_f32_16x16x32_bf16 v[98:101], v[184:187], v[216:219], v[98:101]
	s_setprio 0
	s_barrier
; #define PG8_STAGE(bufoff, gbase, voff) do { _Pragma("unroll") for (int _i = 0; _i < 2; ++_i) \
;         __builtin_amdgcn_global_load_lds((const unsigned*)((const char*)(gbase) + (voff)[_i]), (PG8_LAS unsigned*)(lds + (bufoff) + ldsw + _i * 8192), 16, 0, 0); } while (0)
; #define PG8_LDA(dst, b, h) do { _Pragma("unroll") for (int m = 0; m < 4; ++m) _Pragma("unroll") for (int k = 0; k < 2; ++k) dst[m][k] = *(const PG8_LAS bf16x8*)(lds + PG8_SA(b, h) + aoff + m * 2048 + k * 1024); } while (0)
; #define PG8_MMA(ai, bj, At, Bt) do { __builtin_amdgcn_s_setprio(1); _Pragma("unroll") for (int m = 0; m < 4; ++m) _Pragma("unroll") for (int n = 0; n < 2; ++n) _Pragma("unroll") for (int k = 0; k < 2; ++k) \
;         acc[ai][bj][m][n] = __builtin_amdgcn_mfma_f32_16x16x32_bf16(Bt[n][k], At[m][k], acc[ai][bj][m][n], 0, 0, 0); __builtin_amdgcn_s_setprio(0); } while (0)
; #define PG8_WAIT_V(n) asm volatile("s_waitcnt vmcnt(" #n ")" ::: "memory")
; #define PG8_WAIT_L(n) asm volatile("s_waitcnt lgkmcnt(" #n ")" ::: "memory")
; #define PG8_BAR __builtin_amdgcn_s_barrier()
; #define PG8_SCHED __builtin_amdgcn_sched_barrier(0)
; template <class Epi, class Sched, bool ALIGN_EPI = false, bool SP2 = false>
; __device__ __forceinline__ void gemm_phase(PG8_LAS unsigned char* lds, const Gemm g, const Sched& S, const Epi& E) {
;     ...
;         for (int t = 0; t < nt; t += 2) {
;             const bool last = (t == nt - 2);
;     ...
;             PG8_LDA(At, 1, 1); PG8_STAGE(PG8_SB(1, 0), b3, voffB); PG8_STAGE(PG8_SB(1, 1), b3 + hstep, voffB); PG8_STAGE(PG8_SA(1, 0), a3, voffA);
;             PG8_WAIT_V(8); PG8_WAIT_L(0); PG8_BAR; PG8_MMA(1, 0, At, B0); PG8_MMA(1, 1, At, B1); PG8_BAR; PG8_SCHED;
	s_add_i32 s34, s55, s39
	v_lshl_add_u64 v[146:147], v[146:147], 0, s[96:97]
	s_mov_b32 m0, s34
	ds_read_b128 v[188:191], v153 offset:49152
	ds_read_b128 v[192:195], v153 offset:50176
	ds_read_b128 v[196:199], v153 offset:51200
	ds_read_b128 v[200:203], v153 offset:52224
	ds_read_b128 v[204:207], v153 offset:53248
	ds_read_b128 v[208:211], v153 offset:54272
	ds_read_b128 v[212:215], v153 offset:55296
	ds_read_b128 v[216:219], v153 offset:56320
	global_load_lds_dwordx4 v[146:147], off
	s_add_i32 m0, s34, 0x2000
	s_add_u32 s30, s30, 0x40080
	v_lshl_add_u64 v[146:147], v[220:221], 0, s[96:97]
	s_addc_u32 s31, s31, 0
	s_add_i32 s34, s56, s39
	global_load_lds_dwordx4 v[146:147], off
	v_lshl_add_u64 v[146:147], s[30:31], 0, v[138:139]
	s_mov_b32 m0, s34
	s_nop 0
	global_load_lds_dwordx4 v[146:147], off
	v_lshl_add_u64 v[146:147], s[30:31], 0, v[134:135]
	s_add_i32 m0, s34, 0x2000
	s_nop 0
	global_load_lds_dwordx4 v[146:147], off
	v_lshl_add_u64 v[146:147], v[222:223], 0, s[96:97]
	s_mov_b32 m0, s48
	s_nop 0
	global_load_lds_dwordx4 v[146:147], off
	v_lshl_add_u64 v[146:147], v[228:229], 0, s[96:97]
	s_mov_b32 m0, s49
	s_nop 0
	global_load_lds_dwordx4 v[146:147], off
	s_waitcnt vmcnt(8)
	s_waitcnt lgkmcnt(0)
	s_barrier
	s_setprio 1
	v_mfma_f32_16x16x32_bf16 v[30:33], v[130:133], v[188:191], v[30:33]
	v_mfma_f32_16x16x32_bf16 v[26:29], v[158:161], v[188:191], v[26:29]
	v_mfma_f32_16x16x32_bf16 v[22:25], v[130:133], v[196:199], v[22:25]
	v_mfma_f32_16x16x32_bf16 v[18:21], v[158:161], v[196:199], v[18:21]
	v_mfma_f32_16x16x32_bf16 v[14:17], v[130:133], v[204:207], v[14:17]
	v_mfma_f32_16x16x32_bf16 v[10:13], v[158:161], v[204:207], v[10:13]
	v_mfma_f32_16x16x32_bf16 v[6:9], v[130:133], v[212:215], v[6:9]
	v_mfma_f32_16x16x32_bf16 v[2:5], v[158:161], v[212:215], v[2:5]
	v_mfma_f32_16x16x32_bf16 v[30:33], v[154:157], v[192:195], v[30:33]
	v_mfma_f32_16x16x32_bf16 v[26:29], v[162:165], v[192:195], v[26:29]
	v_mfma_f32_16x16x32_bf16 v[22:25], v[154:157], v[200:203], v[22:25]
	v_mfma_f32_16x16x32_bf16 v[18:21], v[162:165], v[200:203], v[18:21]
	v_mfma_f32_16x16x32_bf16 v[14:17], v[154:157], v[208:211], v[14:17]
	v_mfma_f32_16x16x32_bf16 v[10:13], v[162:165], v[208:211], v[10:13]
	v_mfma_f32_16x16x32_bf16 v[6:9], v[154:157], v[216:219], v[6:9]
	v_mfma_f32_16x16x32_bf16 v[2:5], v[162:165], v[216:219], v[2:5]
	v_mfma_f32_16x16x32_bf16 v[94:97], v[166:169], v[188:191], v[94:97]
	v_mfma_f32_16x16x32_bf16 v[90:93], v[180:183], v[188:191], v[90:93]
	v_mfma_f32_16x16x32_bf16 v[86:89], v[166:169], v[196:199], v[86:89]
	v_mfma_f32_16x16x32_bf16 v[82:85], v[180:183], v[196:199], v[82:85]
	v_mfma_f32_16x16x32_bf16 v[78:81], v[166:169], v[204:207], v[78:81]
	v_mfma_f32_16x16x32_bf16 v[74:77], v[180:183], v[204:207], v[74:77]
	v_mfma_f32_16x16x32_bf16 v[38:41], v[166:169], v[212:215], v[38:41]
	v_mfma_f32_16x16x32_bf16 v[34:37], v[180:183], v[212:215], v[34:37]
	v_mfma_f32_16x16x32_bf16 v[94:97], v[170:173], v[192:195], v[94:97]
	v_mfma_f32_16x16x32_bf16 v[90:93], v[184:187], v[192:195], v[90:93]
	v_mfma_f32_16x16x32_bf16 v[86:89], v[170:173], v[200:203], v[86:89]
	v_mfma_f32_16x16x32_bf16 v[82:85], v[184:187], v[200:203], v[82:85]
	v_mfma_f32_16x16x32_bf16 v[78:81], v[170:173], v[208:211], v[78:81]
	v_mfma_f32_16x16x32_bf16 v[74:77], v[184:187], v[208:211], v[74:77]
	v_mfma_f32_16x16x32_bf16 v[38:41], v[170:173], v[216:219], v[38:41]
	v_mfma_f32_16x16x32_bf16 v[34:37], v[184:187], v[216:219], v[34:37]
	s_setprio 0
	s_barrier
	s_add_i32 s54, s54, 2
	s_add_u32 s28, s28, 0x100
	s_addc_u32 s29, s29, 0
	s_add_u32 s52, s52, 0x100
	s_addc_u32 s53, s53, 0
	s_cmp_gt_u32 s54, 13
	s_cbranch_scc0 .LBB0_185
	s_and_b64 vcc, exec, s[16:17]
	s_cbranch_vccz .LBB0_188
	s_barrier

; #define PG8_STAGE(bufoff, gbase, voff) do { _Pragma("unroll") for (int _i = 0; _i < 2; ++_i) \
;         __builtin_amdgcn_global_load_lds((const unsigned*)((const char*)(gbase) + (voff)[_i]), (PG8_LAS unsigned*)(lds + (bufoff) + ldsw + _i * 8192), 16, 0, 0); } while (0)
; #define PG8_LDA(dst, b, h) do { _Pragma("unroll") for (int m = 0; m < 4; ++m) _Pragma("unroll") for (int k = 0; k < 2; ++k) dst[m][k] = *(const PG8_LAS bf16x8*)(lds + PG8_SA(b, h) + aoff + m * 2048 + k * 1024); } while (0)
; #define PG8_MMA(ai, bj, At, Bt) do { __builtin_amdgcn_s_setprio(1); _Pragma("unroll") for (int m = 0; m < 4; ++m) _Pragma("unroll") for (int n = 0; n < 2; ++n) _Pragma("unroll") for (int k = 0; k < 2; ++k) \
;         acc[ai][bj][m][n] = __builtin_amdgcn_mfma_f32_16x16x32_bf16(Bt[n][k], At[m][k], acc[ai][bj][m][n], 0, 0, 0); __builtin_amdgcn_s_setprio(0); } while (0)
; #define PG8_WAIT_V(n) asm volatile("s_waitcnt vmcnt(" #n ")" ::: "memory")
; #define PG8_WAIT_L(n) asm volatile("s_waitcnt lgkmcnt(" #n ")" ::: "memory")
; #define PG8_BAR __builtin_amdgcn_s_barrier()
; #define PG8_SCHED __builtin_amdgcn_sched_barrier(0)
; template <class Epi, class Sched, bool ALIGN_EPI = false, bool SP2 = false>
; __device__ __forceinline__ void gemm_phase(PG8_LAS unsigned char* lds, const Gemm g, const Sched& S, const Epi& E) {
;     ...
;             PG8_WAIT_V(8); PG8_WAIT_L(0); PG8_BAR; PG8_MMA(0, 0, At, B0); PG8_MMA(0, 1, At, B1); PG8_BAR; PG8_SCHED;
;             PG8_LDA(At, 0, 1); PG8_STAGE(PG8_SB(0, 0), b2, voffB); PG8_STAGE(PG8_SB(0, 1), b2 + hstep, voffB); PG8_STAGE(PG8_SA(0, 0), a2, voffA);
;             PG8_WAIT_V(8); PG8_WAIT_L(0); PG8_BAR; PG8_MMA(1, 0, At, B0); PG8_MMA(1, 1, At, B1); PG8_BAR; PG8_SCHED;
.Lodout_noz:
	s_waitcnt vmcnt(8)
	s_waitcnt lgkmcnt(0)
	s_barrier
	s_setprio 1
	v_mfma_f32_16x16x32_bf16 v[158:161], v[66:69], v[162:165], v[158:161]
	v_mfma_f32_16x16x32_bf16 v[154:157], v[82:85], v[162:165], v[154:157]
	v_mfma_f32_16x16x32_bf16 v[142:145], v[66:69], v[188:191], v[142:145]
	v_mfma_f32_16x16x32_bf16 v[138:141], v[82:85], v[188:191], v[138:141]
	v_mfma_f32_16x16x32_bf16 v[114:117], v[66:69], v[196:199], v[114:117]
	v_mfma_f32_16x16x32_bf16 v[110:113], v[82:85], v[196:199], v[110:113]
	v_mfma_f32_16x16x32_bf16 v[90:93], v[66:69], v[210:213], v[90:93]
	v_mfma_f32_16x16x32_bf16 v[86:89], v[82:85], v[210:213], v[86:89]
	v_mfma_f32_16x16x32_bf16 v[158:161], v[70:73], v[166:169], v[158:161]
	v_mfma_f32_16x16x32_bf16 v[154:157], v[94:97], v[166:169], v[154:157]
	v_mfma_f32_16x16x32_bf16 v[142:145], v[70:73], v[192:195], v[142:145]
	v_mfma_f32_16x16x32_bf16 v[138:141], v[94:97], v[192:195], v[138:141]
	v_mfma_f32_16x16x32_bf16 v[114:117], v[70:73], v[206:209], v[114:117]
	v_mfma_f32_16x16x32_bf16 v[110:113], v[94:97], v[206:209], v[110:113]
	v_mfma_f32_16x16x32_bf16 v[90:93], v[70:73], v[214:217], v[90:93]
	v_mfma_f32_16x16x32_bf16 v[86:89], v[94:97], v[214:217], v[86:89]
	v_mfma_f32_16x16x32_bf16 v[150:153], v[106:109], v[162:165], v[150:153]
	v_mfma_f32_16x16x32_bf16 v[146:149], v[130:133], v[162:165], v[146:149]
	v_mfma_f32_16x16x32_bf16 v[126:129], v[106:109], v[188:191], v[126:129]
	v_mfma_f32_16x16x32_bf16 v[122:125], v[130:133], v[188:191], v[122:125]
	v_mfma_f32_16x16x32_bf16 v[102:105], v[106:109], v[196:199], v[102:105]
	v_mfma_f32_16x16x32_bf16 v[98:101], v[130:133], v[196:199], v[98:101]
	v_mfma_f32_16x16x32_bf16 v[78:81], v[106:109], v[210:213], v[78:81]
	v_mfma_f32_16x16x32_bf16 v[74:77], v[130:133], v[210:213], v[74:77]
	v_mfma_f32_16x16x32_bf16 v[150:153], v[118:121], v[166:169], v[150:153]
	v_mfma_f32_16x16x32_bf16 v[146:149], v[134:137], v[166:169], v[146:149]
	v_mfma_f32_16x16x32_bf16 v[126:129], v[118:121], v[192:195], v[126:129]
	v_mfma_f32_16x16x32_bf16 v[122:125], v[134:137], v[192:195], v[122:125]
	v_mfma_f32_16x16x32_bf16 v[102:105], v[118:121], v[206:209], v[102:105]
	v_mfma_f32_16x16x32_bf16 v[98:101], v[134:137], v[206:209], v[98:101]
	v_mfma_f32_16x16x32_bf16 v[78:81], v[118:121], v[214:217], v[78:81]
	v_mfma_f32_16x16x32_bf16 v[74:77], v[134:137], v[214:217], v[74:77]
	s_setprio 0
	s_barrier
	s_add_i32 s56, s56, s42
	v_lshl_add_u64 v[200:201], s[12:13], 0, v[180:181]
	s_mov_b32 m0, s56
	ds_read_b128 v[162:165], v204 offset:16384
	ds_read_b128 v[166:169], v204 offset:17408
	ds_read_b128 v[188:191], v204 offset:18432
	ds_read_b128 v[192:195], v204 offset:19456
	ds_read_b128 v[196:199], v204 offset:20480
	ds_read_b128 v[206:209], v204 offset:21504
	ds_read_b128 v[210:213], v204 offset:22528
	ds_read_b128 v[214:217], v204 offset:23552
	global_load_lds_dwordx4 v[200:201], off
	s_add_i32 m0, s56, 0x2000
	s_add_u32 s56, s12, 0x40000
	v_lshl_add_u64 v[218:219], s[12:13], 0, v[170:171]
	s_addc_u32 s57, s13, 0
	s_add_i32 s58, s58, s42
	global_load_lds_dwordx4 v[218:219], off
	v_lshl_add_u64 v[220:221], s[56:57], 0, v[180:181]
	s_mov_b32 m0, s58
	v_lshl_add_u64 v[222:223], s[36:37], 0, v[172:173]
	global_load_lds_dwordx4 v[220:221], off
	v_lshl_add_u64 v[220:221], s[56:57], 0, v[170:171]
	s_add_i32 m0, s58, 0x2000
	s_nop 0
	global_load_lds_dwordx4 v[220:221], off
	v_lshl_add_u64 v[220:221], s[36:37], 0, v[182:183]
	s_mov_b32 m0, s43
	s_nop 0
	global_load_lds_dwordx4 v[220:221], off
	s_mov_b32 m0, s44
	s_nop 0
	global_load_lds_dwordx4 v[222:223], off
	s_waitcnt vmcnt(8)
	s_waitcnt lgkmcnt(0)
	s_barrier
	s_setprio 1
	v_mfma_f32_16x16x32_bf16 v[62:65], v[66:69], v[162:165], v[62:65]
	v_mfma_f32_16x16x32_bf16 v[58:61], v[82:85], v[162:165], v[58:61]
	v_mfma_f32_16x16x32_bf16 v[46:49], v[66:69], v[188:191], v[46:49]
	v_mfma_f32_16x16x32_bf16 v[42:45], v[82:85], v[188:191], v[42:45]
	v_mfma_f32_16x16x32_bf16 v[30:33], v[66:69], v[196:199], v[30:33]
	v_mfma_f32_16x16x32_bf16 v[26:29], v[82:85], v[196:199], v[26:29]
	v_mfma_f32_16x16x32_bf16 v[14:17], v[66:69], v[210:213], v[14:17]
	v_mfma_f32_16x16x32_bf16 v[10:13], v[82:85], v[210:213], v[10:13]
	v_mfma_f32_16x16x32_bf16 v[62:65], v[70:73], v[166:169], v[62:65]
	v_mfma_f32_16x16x32_bf16 v[58:61], v[94:97], v[166:169], v[58:61]
	v_mfma_f32_16x16x32_bf16 v[46:49], v[70:73], v[192:195], v[46:49]
	v_mfma_f32_16x16x32_bf16 v[42:45], v[94:97], v[192:195], v[42:45]
	v_mfma_f32_16x16x32_bf16 v[30:33], v[70:73], v[206:209], v[30:33]
	v_mfma_f32_16x16x32_bf16 v[26:29], v[94:97], v[206:209], v[26:29]
	v_mfma_f32_16x16x32_bf16 v[14:17], v[70:73], v[214:217], v[14:17]
	v_mfma_f32_16x16x32_bf16 v[10:13], v[94:97], v[214:217], v[10:13]
	v_mfma_f32_16x16x32_bf16 v[54:57], v[106:109], v[162:165], v[54:57]
	v_mfma_f32_16x16x32_bf16 v[50:53], v[130:133], v[162:165], v[50:53]
	v_mfma_f32_16x16x32_bf16 v[38:41], v[106:109], v[188:191], v[38:41]
	v_mfma_f32_16x16x32_bf16 v[34:37], v[130:133], v[188:191], v[34:37]
	v_mfma_f32_16x16x32_bf16 v[22:25], v[106:109], v[196:199], v[22:25]
	v_mfma_f32_16x16x32_bf16 v[18:21], v[130:133], v[196:199], v[18:21]
	v_mfma_f32_16x16x32_bf16 v[6:9], v[106:109], v[210:213], v[6:9]
	v_mfma_f32_16x16x32_bf16 v[2:5], v[130:133], v[210:213], v[2:5]
	v_mfma_f32_16x16x32_bf16 v[54:57], v[118:121], v[166:169], v[54:57]
	v_mfma_f32_16x16x32_bf16 v[50:53], v[134:137], v[166:169], v[50:53]
	v_mfma_f32_16x16x32_bf16 v[38:41], v[118:121], v[192:195], v[38:41]
	v_mfma_f32_16x16x32_bf16 v[34:37], v[134:137], v[192:195], v[34:37]
	v_mfma_f32_16x16x32_bf16 v[22:25], v[118:121], v[206:209], v[22:25]
	v_mfma_f32_16x16x32_bf16 v[18:21], v[134:137], v[206:209], v[18:21]
	v_mfma_f32_16x16x32_bf16 v[6:9], v[118:121], v[214:217], v[6:9]
	v_mfma_f32_16x16x32_bf16 v[2:5], v[134:137], v[214:217], v[2:5]
	s_setprio 0
	s_barrier
; #define PG8_STAGE(bufoff, gbase, voff) do { _Pragma("unroll") for (int _i = 0; _i < 2; ++_i) \
;         __builtin_amdgcn_global_load_lds((const unsigned*)((const char*)(gbase) + (voff)[_i]), (PG8_LAS unsigned*)(lds + (bufoff) + ldsw + _i * 8192), 16, 0, 0); } while (0)
; #define PG8_LDA(dst, b, h) do { _Pragma("unroll") for (int m = 0; m < 4; ++m) _Pragma("unroll") for (int k = 0; k < 2; ++k) dst[m][k] = *(const PG8_LAS bf16x8*)(lds + PG8_SA(b, h) + aoff + m * 2048 + k * 1024); } while (0)
; #define PG8_LDB(dst, b, h) do { _Pragma("unroll") for (int n = 0; n < 2; ++n) _Pragma("unroll") for (int k = 0; k < 2; ++k) dst[n][k] = *(const PG8_LAS bf16x8*)(lds + PG8_SB(b, h) + boff + n * 2048 + k * 1024); } while (0)
; #define PG8_MMA(ai, bj, At, Bt) do { __builtin_amdgcn_s_setprio(1); _Pragma("unroll") for (int m = 0; m < 4; ++m) _Pragma("unroll") for (int n = 0; n < 2; ++n) _Pragma("unroll") for (int k = 0; k < 2; ++k) \
;         acc[ai][bj][m][n] = __builtin_amdgcn_mfma_f32_16x16x32_bf16(Bt[n][k], At[m][k], acc[ai][bj][m][n], 0, 0, 0); __builtin_amdgcn_s_setprio(0); } while (0)
; #define PG8_WAIT_V(n) asm volatile("s_waitcnt vmcnt(" #n ")" ::: "memory")
; #define PG8_WAIT_L(n) asm volatile("s_waitcnt lgkmcnt(" #n ")" ::: "memory")
; #define PG8_BAR __builtin_amdgcn_s_barrier()
; #define PG8_SCHED __builtin_amdgcn_sched_barrier(0)
; template <class Epi, class Sched, bool ALIGN_EPI = false, bool SP2 = false>
; __device__ __forceinline__ void gemm_phase(PG8_LAS unsigned char* lds, const Gemm g, const Sched& S, const Epi& E) {
;     ...
;             PG8_LDB(B0, 1, 0); PG8_LDB(B1, 1, 1); PG8_SCHED; PG8_LDA(At, 1, 0); PG8_STAGE(PG8_SA(0, 1), a2 + hstep, voffA);
;             PG8_WAIT_V(8); PG8_WAIT_L(0); PG8_BAR; PG8_MMA(0, 0, At, B0); PG8_MMA(0, 1, At, B1); PG8_BAR; PG8_SCHED;
	s_add_i32 s56, 0, 0x18000
	s_add_i32 s57, 0, 0x1c000
	v_add_u32_e32 v94, s56, v203
	v_add_u32_e32 v134, s57, v203
	ds_read_b128 v[66:69], v94
	ds_read_b128 v[70:73], v94 offset:1024
	ds_read_b128 v[82:85], v94 offset:2048
	ds_read_b128 v[94:97], v94 offset:3072
	ds_read_b128 v[106:109], v134
	ds_read_b128 v[118:121], v134 offset:1024
	ds_read_b128 v[130:133], v134 offset:2048
	ds_read_b128 v[134:137], v134 offset:3072
	s_add_u32 s36, s36, 0x40000
	s_addc_u32 s37, s37, 0
	s_mov_b32 m0, s45
	v_lshl_add_u64 v[228:229], s[36:37], 0, v[182:183]
	ds_read_b128 v[162:165], v204 offset:32768
	ds_read_b128 v[166:169], v204 offset:33792
	ds_read_b128 v[188:191], v204 offset:34816
	ds_read_b128 v[192:195], v204 offset:35840
	ds_read_b128 v[196:199], v204 offset:36864
	ds_read_b128 v[206:209], v204 offset:37888
	ds_read_b128 v[210:213], v204 offset:38912
	ds_read_b128 v[214:217], v204 offset:39936
	global_load_lds_dwordx4 v[228:229], off
	v_lshl_add_u64 v[228:229], s[36:37], 0, v[172:173]
	s_mov_b32 m0, s46
	s_nop 0
	global_load_lds_dwordx4 v[228:229], off
	s_waitcnt vmcnt(8)
	s_waitcnt lgkmcnt(0)
	s_barrier
	s_setprio 1
	v_mfma_f32_16x16x32_bf16 v[158:161], v[66:69], v[162:165], v[158:161]
	v_mfma_f32_16x16x32_bf16 v[154:157], v[82:85], v[162:165], v[154:157]
	v_mfma_f32_16x16x32_bf16 v[142:145], v[66:69], v[188:191], v[142:145]
	v_mfma_f32_16x16x32_bf16 v[138:141], v[82:85], v[188:191], v[138:141]
	v_mfma_f32_16x16x32_bf16 v[114:117], v[66:69], v[196:199], v[114:117]
	v_mfma_f32_16x16x32_bf16 v[110:113], v[82:85], v[196:199], v[110:113]
	v_mfma_f32_16x16x32_bf16 v[90:93], v[66:69], v[210:213], v[90:93]
	v_mfma_f32_16x16x32_bf16 v[86:89], v[82:85], v[210:213], v[86:89]
	v_mfma_f32_16x16x32_bf16 v[158:161], v[70:73], v[166:169], v[158:161]
	v_mfma_f32_16x16x32_bf16 v[154:157], v[94:97], v[166:169], v[154:157]
	v_mfma_f32_16x16x32_bf16 v[142:145], v[70:73], v[192:195], v[142:145]
	v_mfma_f32_16x16x32_bf16 v[138:141], v[94:97], v[192:195], v[138:141]
	v_mfma_f32_16x16x32_bf16 v[114:117], v[70:73], v[206:209], v[114:117]
	v_mfma_f32_16x16x32_bf16 v[110:113], v[94:97], v[206:209], v[110:113]
	v_mfma_f32_16x16x32_bf16 v[90:93], v[70:73], v[214:217], v[90:93]
	v_mfma_f32_16x16x32_bf16 v[86:89], v[94:97], v[214:217], v[86:89]
	v_mfma_f32_16x16x32_bf16 v[150:153], v[106:109], v[162:165], v[150:153]
	v_mfma_f32_16x16x32_bf16 v[146:149], v[130:133], v[162:165], v[146:149]
	v_mfma_f32_16x16x32_bf16 v[126:129], v[106:109], v[188:191], v[126:129]
	v_mfma_f32_16x16x32_bf16 v[122:125], v[130:133], v[188:191], v[122:125]
	v_mfma_f32_16x16x32_bf16 v[102:105], v[106:109], v[196:199], v[102:105]
	v_mfma_f32_16x16x32_bf16 v[98:101], v[130:133], v[196:199], v[98:101]
	v_mfma_f32_16x16x32_bf16 v[78:81], v[106:109], v[210:213], v[78:81]
	v_mfma_f32_16x16x32_bf16 v[74:77], v[130:133], v[210:213], v[74:77]
	v_mfma_f32_16x16x32_bf16 v[150:153], v[118:121], v[166:169], v[150:153]
	v_mfma_f32_16x16x32_bf16 v[146:149], v[134:137], v[166:169], v[146:149]
	v_mfma_f32_16x16x32_bf16 v[126:129], v[118:121], v[192:195], v[126:129]
	v_mfma_f32_16x16x32_bf16 v[122:125], v[134:137], v[192:195], v[122:125]
	v_mfma_f32_16x16x32_bf16 v[102:105], v[118:121], v[206:209], v[102:105]
	v_mfma_f32_16x16x32_bf16 v[98:101], v[134:137], v[206:209], v[98:101]
	v_mfma_f32_16x16x32_bf16 v[78:81], v[118:121], v[214:217], v[78:81]
	v_mfma_f32_16x16x32_bf16 v[74:77], v[134:137], v[214:217], v[74:77]
	s_setprio 0
	s_barrier
; #define PG8_STAGE(bufoff, gbase, voff) do { _Pragma("unroll") for (int _i = 0; _i < 2; ++_i) \
;         __builtin_amdgcn_global_load_lds((const unsigned*)((const char*)(gbase) + (voff)[_i]), (PG8_LAS unsigned*)(lds + (bufoff) + ldsw + _i * 8192), 16, 0, 0); } while (0)
; #define PG8_LDA(dst, b, h) do { _Pragma("unroll") for (int m = 0; m < 4; ++m) _Pragma("unroll") for (int k = 0; k < 2; ++k) dst[m][k] = *(const PG8_LAS bf16x8*)(lds + PG8_SA(b, h) + aoff + m * 2048 + k * 1024); } while (0)
; #define PG8_MMA(ai, bj, At, Bt) do { __builtin_amdgcn_s_setprio(1); _Pragma("unroll") for (int m = 0; m < 4; ++m) _Pragma("unroll") for (int n = 0; n < 2; ++n) _Pragma("unroll") for (int k = 0; k < 2; ++k) \
;         acc[ai][bj][m][n] = __builtin_amdgcn_mfma_f32_16x16x32_bf16(Bt[n][k], At[m][k], acc[ai][bj][m][n], 0, 0, 0); __builtin_amdgcn_s_setprio(0); } while (0)
; #define PG8_WAIT_V(n) asm volatile("s_waitcnt vmcnt(" #n ")" ::: "memory")
; #define PG8_WAIT_L(n) asm volatile("s_waitcnt lgkmcnt(" #n ")" ::: "memory")
; #define PG8_BAR __builtin_amdgcn_s_barrier()
; #define PG8_SCHED __builtin_amdgcn_sched_barrier(0)
; template <class Epi, class Sched, bool ALIGN_EPI = false, bool SP2 = false>
; __device__ __forceinline__ void gemm_phase(PG8_LAS unsigned char* lds, const Gemm g, const Sched& S, const Epi& E) {
;     ...
;         for (int t = 0; t < nt; t += 2) {
;     ...
;             PG8_LDA(At, 1, 1); PG8_STAGE(PG8_SB(1, 0), b3, voffB); PG8_STAGE(PG8_SB(1, 1), b3 + hstep, voffB); PG8_STAGE(PG8_SA(1, 0), a3, voffA);
;             PG8_WAIT_V(8); PG8_WAIT_L(0); PG8_BAR; PG8_MMA(1, 0, At, B0); PG8_MMA(1, 1, At, B1); PG8_BAR; PG8_SCHED;
	s_add_i32 s36, s56, s42
	v_lshl_add_u64 v[200:201], v[200:201], 0, s[96:97]
	s_mov_b32 m0, s36
	ds_read_b128 v[162:165], v204 offset:49152
	ds_read_b128 v[166:169], v204 offset:50176
	ds_read_b128 v[188:191], v204 offset:51200
	ds_read_b128 v[192:195], v204 offset:52224
	ds_read_b128 v[196:199], v204 offset:53248
	ds_read_b128 v[206:209], v204 offset:54272
	ds_read_b128 v[210:213], v204 offset:55296
	ds_read_b128 v[214:217], v204 offset:56320
	global_load_lds_dwordx4 v[200:201], off
	s_add_i32 m0, s36, 0x2000
	s_add_u32 s12, s12, 0x40080
	v_lshl_add_u64 v[200:201], v[218:219], 0, s[96:97]
	s_addc_u32 s13, s13, 0
	s_add_i32 s36, s57, s42
	global_load_lds_dwordx4 v[200:201], off
	v_lshl_add_u64 v[200:201], s[12:13], 0, v[180:181]
	s_mov_b32 m0, s36
	s_nop 0
	global_load_lds_dwordx4 v[200:201], off
	v_lshl_add_u64 v[200:201], s[12:13], 0, v[170:171]
	s_add_i32 m0, s36, 0x2000
	s_nop 0
	global_load_lds_dwordx4 v[200:201], off
	v_lshl_add_u64 v[200:201], v[220:221], 0, s[96:97]
	s_mov_b32 m0, s50
	s_nop 0
	global_load_lds_dwordx4 v[200:201], off
	v_lshl_add_u64 v[200:201], v[222:223], 0, s[96:97]
	s_mov_b32 m0, s51
	s_nop 0
	global_load_lds_dwordx4 v[200:201], off
	s_waitcnt vmcnt(8)
	s_waitcnt lgkmcnt(0)
	s_barrier
	s_setprio 1
	v_mfma_f32_16x16x32_bf16 v[62:65], v[66:69], v[162:165], v[62:65]
	v_mfma_f32_16x16x32_bf16 v[58:61], v[82:85], v[162:165], v[58:61]
	v_mfma_f32_16x16x32_bf16 v[46:49], v[66:69], v[188:191], v[46:49]
	v_mfma_f32_16x16x32_bf16 v[42:45], v[82:85], v[188:191], v[42:45]
	v_mfma_f32_16x16x32_bf16 v[30:33], v[66:69], v[196:199], v[30:33]
	v_mfma_f32_16x16x32_bf16 v[26:29], v[82:85], v[196:199], v[26:29]
	v_mfma_f32_16x16x32_bf16 v[14:17], v[66:69], v[210:213], v[14:17]
	v_mfma_f32_16x16x32_bf16 v[10:13], v[82:85], v[210:213], v[10:13]
	v_mfma_f32_16x16x32_bf16 v[62:65], v[70:73], v[166:169], v[62:65]
	v_mfma_f32_16x16x32_bf16 v[58:61], v[94:97], v[166:169], v[58:61]
	v_mfma_f32_16x16x32_bf16 v[46:49], v[70:73], v[192:195], v[46:49]
	v_mfma_f32_16x16x32_bf16 v[42:45], v[94:97], v[192:195], v[42:45]
	v_mfma_f32_16x16x32_bf16 v[30:33], v[70:73], v[206:209], v[30:33]
	v_mfma_f32_16x16x32_bf16 v[26:29], v[94:97], v[206:209], v[26:29]
	v_mfma_f32_16x16x32_bf16 v[14:17], v[70:73], v[214:217], v[14:17]
	v_mfma_f32_16x16x32_bf16 v[10:13], v[94:97], v[214:217], v[10:13]
	v_mfma_f32_16x16x32_bf16 v[54:57], v[106:109], v[162:165], v[54:57]
	v_mfma_f32_16x16x32_bf16 v[50:53], v[130:133], v[162:165], v[50:53]
	v_mfma_f32_16x16x32_bf16 v[38:41], v[106:109], v[188:191], v[38:41]
	v_mfma_f32_16x16x32_bf16 v[34:37], v[130:133], v[188:191], v[34:37]
	v_mfma_f32_16x16x32_bf16 v[22:25], v[106:109], v[196:199], v[22:25]
	v_mfma_f32_16x16x32_bf16 v[18:21], v[130:133], v[196:199], v[18:21]
	v_mfma_f32_16x16x32_bf16 v[6:9], v[106:109], v[210:213], v[6:9]
	v_mfma_f32_16x16x32_bf16 v[2:5], v[130:133], v[210:213], v[2:5]
	v_mfma_f32_16x16x32_bf16 v[54:57], v[118:121], v[166:169], v[54:57]
	v_mfma_f32_16x16x32_bf16 v[50:53], v[134:137], v[166:169], v[50:53]
	v_mfma_f32_16x16x32_bf16 v[38:41], v[118:121], v[192:195], v[38:41]
	v_mfma_f32_16x16x32_bf16 v[34:37], v[134:137], v[192:195], v[34:37]
	v_mfma_f32_16x16x32_bf16 v[22:25], v[118:121], v[206:209], v[22:25]
	v_mfma_f32_16x16x32_bf16 v[18:21], v[134:137], v[206:209], v[18:21]
	v_mfma_f32_16x16x32_bf16 v[6:9], v[118:121], v[214:217], v[6:9]
	v_mfma_f32_16x16x32_bf16 v[2:5], v[134:137], v[214:217], v[2:5]
	s_setprio 0
	s_barrier
	s_add_i32 s55, s55, 2
	s_add_u32 s10, s10, 0x100
	s_addc_u32 s11, s11, 0
	s_add_u32 s33, s33, 0x100
	s_addc_u32 s54, s54, 0
	s_cmp_gt_u32 s55, 13
	s_cbranch_scc0 .LBB0_633
	s_and_b64 vcc, exec, s[20:21]
	s_cbranch_vccz .LBB0_636
	s_barrier

; #define PG8_STAGE(bufoff, gbase, voff) do { _Pragma("unroll") for (int _i = 0; _i < 2; ++_i) \
;         __builtin_amdgcn_global_load_lds((const unsigned*)((const char*)(gbase) + (voff)[_i]), (PG8_LAS unsigned*)(lds + (bufoff) + ldsw + _i * 8192), 16, 0, 0); } while (0)
; #define PG8_LDA(dst, b, h) do { _Pragma("unroll") for (int m = 0; m < 4; ++m) _Pragma("unroll") for (int k = 0; k < 2; ++k) dst[m][k] = *(const PG8_LAS bf16x8*)(lds + PG8_SA(b, h) + aoff + m * 2048 + k * 1024); } while (0)
; #define PG8_MMA(ai, bj, At, Bt) do { __builtin_amdgcn_s_setprio(1); _Pragma("unroll") for (int m = 0; m < 4; ++m) _Pragma("unroll") for (int n = 0; n < 2; ++n) _Pragma("unroll") for (int k = 0; k < 2; ++k) \
;         acc[ai][bj][m][n] = __builtin_amdgcn_mfma_f32_16x16x32_bf16(Bt[n][k], At[m][k], acc[ai][bj][m][n], 0, 0, 0); __builtin_amdgcn_s_setprio(0); } while (0)
; #define PG8_WAIT_V(n) asm volatile("s_waitcnt vmcnt(" #n ")" ::: "memory")
; #define PG8_WAIT_L(n) asm volatile("s_waitcnt lgkmcnt(" #n ")" ::: "memory")
; #define PG8_BAR __builtin_amdgcn_s_barrier()
; #define PG8_SCHED __builtin_amdgcn_sched_barrier(0)
; template <class Epi, class Sched, bool ALIGN_EPI = false, bool SP2 = false>
; __device__ __forceinline__ void gemm_phase(PG8_LAS unsigned char* lds, const Gemm g, const Sched& S, const Epi& E) {
;     ...
;             PG8_WAIT_V(8); PG8_WAIT_L(0); PG8_BAR; PG8_MMA(0, 0, At, B0); PG8_MMA(0, 1, At, B1); PG8_BAR; PG8_SCHED;
;             PG8_LDA(At, 0, 1); PG8_STAGE(PG8_SB(0, 0), b2, voffB); PG8_STAGE(PG8_SB(0, 1), b2 + hstep, voffB); PG8_STAGE(PG8_SA(0, 0), a2, voffA);
;             PG8_WAIT_V(8); PG8_WAIT_L(0); PG8_BAR; PG8_MMA(1, 0, At, B0); PG8_MMA(1, 1, At, B1); PG8_BAR; PG8_SCHED;
.Levin_noz:
	s_waitcnt vmcnt(8)
	s_waitcnt lgkmcnt(0)
	s_barrier
	s_setprio 1
	v_mfma_f32_16x16x32_bf16 v[126:129], v[150:153], v[188:191], v[126:129]
	v_mfma_f32_16x16x32_bf16 v[122:125], v[158:161], v[188:191], v[122:125]
	v_mfma_f32_16x16x32_bf16 v[114:117], v[150:153], v[196:199], v[114:117]
	v_mfma_f32_16x16x32_bf16 v[106:109], v[158:161], v[196:199], v[106:109]
	v_mfma_f32_16x16x32_bf16 v[98:101], v[150:153], v[204:207], v[98:101]
	v_mfma_f32_16x16x32_bf16 v[90:93], v[158:161], v[204:207], v[90:93]
	v_mfma_f32_16x16x32_bf16 v[82:85], v[150:153], v[212:215], v[82:85]
	v_mfma_f32_16x16x32_bf16 v[74:77], v[158:161], v[212:215], v[74:77]
	v_mfma_f32_16x16x32_bf16 v[126:129], v[154:157], v[192:195], v[126:129]
	v_mfma_f32_16x16x32_bf16 v[122:125], v[162:165], v[192:195], v[122:125]
	v_mfma_f32_16x16x32_bf16 v[114:117], v[154:157], v[200:203], v[114:117]
	v_mfma_f32_16x16x32_bf16 v[106:109], v[162:165], v[200:203], v[106:109]
	v_mfma_f32_16x16x32_bf16 v[98:101], v[154:157], v[208:211], v[98:101]
	v_mfma_f32_16x16x32_bf16 v[90:93], v[162:165], v[208:211], v[90:93]
	v_mfma_f32_16x16x32_bf16 v[82:85], v[154:157], v[216:219], v[82:85]
	v_mfma_f32_16x16x32_bf16 v[74:77], v[162:165], v[216:219], v[74:77]
	v_mfma_f32_16x16x32_bf16 v[118:121], v[166:169], v[188:191], v[118:121]
	v_mfma_f32_16x16x32_bf16 v[110:113], v[180:183], v[188:191], v[110:113]
	v_mfma_f32_16x16x32_bf16 v[102:105], v[166:169], v[196:199], v[102:105]
	v_mfma_f32_16x16x32_bf16 v[94:97], v[180:183], v[196:199], v[94:97]
	v_mfma_f32_16x16x32_bf16 v[86:89], v[166:169], v[204:207], v[86:89]
	v_mfma_f32_16x16x32_bf16 v[78:81], v[180:183], v[204:207], v[78:81]
	v_mfma_f32_16x16x32_bf16 v[70:73], v[166:169], v[212:215], v[70:73]
	v_mfma_f32_16x16x32_bf16 v[66:69], v[180:183], v[212:215], v[66:69]
	v_mfma_f32_16x16x32_bf16 v[118:121], v[170:173], v[192:195], v[118:121]
	v_mfma_f32_16x16x32_bf16 v[110:113], v[184:187], v[192:195], v[110:113]
	v_mfma_f32_16x16x32_bf16 v[102:105], v[170:173], v[200:203], v[102:105]
	v_mfma_f32_16x16x32_bf16 v[94:97], v[184:187], v[200:203], v[94:97]
	v_mfma_f32_16x16x32_bf16 v[86:89], v[170:173], v[208:211], v[86:89]
	v_mfma_f32_16x16x32_bf16 v[78:81], v[184:187], v[208:211], v[78:81]
	v_mfma_f32_16x16x32_bf16 v[70:73], v[170:173], v[216:219], v[70:73]
	v_mfma_f32_16x16x32_bf16 v[66:69], v[184:187], v[216:219], v[66:69]
	s_setprio 0
	s_barrier
	s_add_i32 s49, s49, s35
	v_lshl_add_u64 v[146:147], s[26:27], 0, v[134:135]
	s_mov_b32 m0, s49
	ds_read_b128 v[188:191], v149 offset:16384
	ds_read_b128 v[192:195], v149 offset:17408
	ds_read_b128 v[196:199], v149 offset:18432
	ds_read_b128 v[200:203], v149 offset:19456
	ds_read_b128 v[204:207], v149 offset:20480
	ds_read_b128 v[208:211], v149 offset:21504
	ds_read_b128 v[212:215], v149 offset:22528
	ds_read_b128 v[216:219], v149 offset:23552
	global_load_lds_dwordx4 v[146:147], off
	s_add_i32 m0, s49, 0x2000
	s_add_u32 s50, s26, 0x40000
	v_lshl_add_u64 v[220:221], s[26:27], 0, v[130:131]
	s_addc_u32 s51, s27, 0
	s_add_i32 s49, s52, s35
	global_load_lds_dwordx4 v[220:221], off
	v_lshl_add_u64 v[222:223], s[50:51], 0, v[134:135]
	s_mov_b32 m0, s49
	v_lshl_add_u64 v[228:229], s[28:29], 0, v[132:133]
	global_load_lds_dwordx4 v[222:223], off
	v_lshl_add_u64 v[222:223], s[50:51], 0, v[130:131]
	s_add_i32 m0, s49, 0x2000
	s_nop 0
	global_load_lds_dwordx4 v[222:223], off
	v_lshl_add_u64 v[222:223], s[28:29], 0, v[136:137]
	s_mov_b32 m0, s36
	s_nop 0
	global_load_lds_dwordx4 v[222:223], off
	s_mov_b32 m0, s37
	s_nop 0
	global_load_lds_dwordx4 v[228:229], off
	s_waitcnt vmcnt(8)
	s_waitcnt lgkmcnt(0)
	s_barrier
	s_setprio 1
	v_mfma_f32_16x16x32_bf16 v[62:65], v[150:153], v[188:191], v[62:65]
	v_mfma_f32_16x16x32_bf16 v[58:61], v[158:161], v[188:191], v[58:61]
	v_mfma_f32_16x16x32_bf16 v[50:53], v[150:153], v[196:199], v[50:53]
	v_mfma_f32_16x16x32_bf16 v[42:45], v[158:161], v[196:199], v[42:45]
	v_mfma_f32_16x16x32_bf16 v[34:37], v[150:153], v[204:207], v[34:37]
	v_mfma_f32_16x16x32_bf16 v[26:29], v[158:161], v[204:207], v[26:29]
	v_mfma_f32_16x16x32_bf16 v[18:21], v[150:153], v[212:215], v[18:21]
	v_mfma_f32_16x16x32_bf16 v[10:13], v[158:161], v[212:215], v[10:13]
	v_mfma_f32_16x16x32_bf16 v[62:65], v[154:157], v[192:195], v[62:65]
	v_mfma_f32_16x16x32_bf16 v[58:61], v[162:165], v[192:195], v[58:61]
	v_mfma_f32_16x16x32_bf16 v[50:53], v[154:157], v[200:203], v[50:53]
	v_mfma_f32_16x16x32_bf16 v[42:45], v[162:165], v[200:203], v[42:45]
	v_mfma_f32_16x16x32_bf16 v[34:37], v[154:157], v[208:211], v[34:37]
	v_mfma_f32_16x16x32_bf16 v[26:29], v[162:165], v[208:211], v[26:29]
	v_mfma_f32_16x16x32_bf16 v[18:21], v[154:157], v[216:219], v[18:21]
	v_mfma_f32_16x16x32_bf16 v[10:13], v[162:165], v[216:219], v[10:13]
	v_mfma_f32_16x16x32_bf16 v[54:57], v[166:169], v[188:191], v[54:57]
	v_mfma_f32_16x16x32_bf16 v[46:49], v[180:183], v[188:191], v[46:49]
	v_mfma_f32_16x16x32_bf16 v[38:41], v[166:169], v[196:199], v[38:41]
	v_mfma_f32_16x16x32_bf16 v[30:33], v[180:183], v[196:199], v[30:33]
	v_mfma_f32_16x16x32_bf16 v[22:25], v[166:169], v[204:207], v[22:25]
	v_mfma_f32_16x16x32_bf16 v[14:17], v[180:183], v[204:207], v[14:17]
	v_mfma_f32_16x16x32_bf16 v[6:9], v[166:169], v[212:215], v[6:9]
	v_mfma_f32_16x16x32_bf16 v[2:5], v[180:183], v[212:215], v[2:5]
	v_mfma_f32_16x16x32_bf16 v[54:57], v[170:173], v[192:195], v[54:57]
	v_mfma_f32_16x16x32_bf16 v[46:49], v[184:187], v[192:195], v[46:49]
	v_mfma_f32_16x16x32_bf16 v[38:41], v[170:173], v[200:203], v[38:41]
	v_mfma_f32_16x16x32_bf16 v[30:33], v[184:187], v[200:203], v[30:33]
	v_mfma_f32_16x16x32_bf16 v[22:25], v[170:173], v[208:211], v[22:25]
	v_mfma_f32_16x16x32_bf16 v[14:17], v[184:187], v[208:211], v[14:17]
	v_mfma_f32_16x16x32_bf16 v[6:9], v[170:173], v[216:219], v[6:9]
	v_mfma_f32_16x16x32_bf16 v[2:5], v[184:187], v[216:219], v[2:5]
	s_setprio 0
	s_barrier
; #define PG8_STAGE(bufoff, gbase, voff) do { _Pragma("unroll") for (int _i = 0; _i < 2; ++_i) \
;         __builtin_amdgcn_global_load_lds((const unsigned*)((const char*)(gbase) + (voff)[_i]), (PG8_LAS unsigned*)(lds + (bufoff) + ldsw + _i * 8192), 16, 0, 0); } while (0)
; #define PG8_LDA(dst, b, h) do { _Pragma("unroll") for (int m = 0; m < 4; ++m) _Pragma("unroll") for (int k = 0; k < 2; ++k) dst[m][k] = *(const PG8_LAS bf16x8*)(lds + PG8_SA(b, h) + aoff + m * 2048 + k * 1024); } while (0)
; #define PG8_LDB(dst, b, h) do { _Pragma("unroll") for (int n = 0; n < 2; ++n) _Pragma("unroll") for (int k = 0; k < 2; ++k) dst[n][k] = *(const PG8_LAS bf16x8*)(lds + PG8_SB(b, h) + boff + n * 2048 + k * 1024); } while (0)
; #define PG8_MMA(ai, bj, At, Bt) do { __builtin_amdgcn_s_setprio(1); _Pragma("unroll") for (int m = 0; m < 4; ++m) _Pragma("unroll") for (int n = 0; n < 2; ++n) _Pragma("unroll") for (int k = 0; k < 2; ++k) \
;         acc[ai][bj][m][n] = __builtin_amdgcn_mfma_f32_16x16x32_bf16(Bt[n][k], At[m][k], acc[ai][bj][m][n], 0, 0, 0); __builtin_amdgcn_s_setprio(0); } while (0)
; #define PG8_WAIT_V(n) asm volatile("s_waitcnt vmcnt(" #n ")" ::: "memory")
; #define PG8_WAIT_L(n) asm volatile("s_waitcnt lgkmcnt(" #n ")" ::: "memory")
; #define PG8_BAR __builtin_amdgcn_s_barrier()
; #define PG8_SCHED __builtin_amdgcn_sched_barrier(0)
; template <class Epi, class Sched, bool ALIGN_EPI = false, bool SP2 = false>
; __device__ __forceinline__ void gemm_phase(PG8_LAS unsigned char* lds, const Gemm g, const Sched& S, const Epi& E) {
;     ...
;             PG8_LDB(B0, 1, 0); PG8_LDB(B1, 1, 1); PG8_SCHED; PG8_LDA(At, 1, 0); PG8_STAGE(PG8_SA(0, 1), a2 + hstep, voffA);
;             PG8_WAIT_V(8); PG8_WAIT_L(0); PG8_BAR; PG8_MMA(0, 0, At, B0); PG8_MMA(0, 1, At, B1); PG8_BAR; PG8_SCHED;
	s_add_i32 s49, 0, 0x18000
	v_add_u32_e32 v142, s49, v145
	s_add_i32 s50, 0, 0x1c000
	ds_read_b128 v[150:153], v142
	ds_read_b128 v[154:157], v142 offset:1024
	ds_read_b128 v[158:161], v142 offset:2048
	ds_read_b128 v[162:165], v142 offset:3072
	v_add_u32_e32 v142, s50, v145
	ds_read_b128 v[166:169], v142
	ds_read_b128 v[170:173], v142 offset:1024
	ds_read_b128 v[180:183], v142 offset:2048
	ds_read_b128 v[184:187], v142 offset:3072
	s_add_u32 s28, s28, 0x40000
	s_addc_u32 s29, s29, 0
	s_mov_b32 m0, s38
	v_lshl_add_u64 v[230:231], s[28:29], 0, v[136:137]
	ds_read_b128 v[188:191], v149 offset:32768
	ds_read_b128 v[192:195], v149 offset:33792
	ds_read_b128 v[196:199], v149 offset:34816
	ds_read_b128 v[200:203], v149 offset:35840
	ds_read_b128 v[204:207], v149 offset:36864
	ds_read_b128 v[208:211], v149 offset:37888
	ds_read_b128 v[212:215], v149 offset:38912
	ds_read_b128 v[216:219], v149 offset:39936
	global_load_lds_dwordx4 v[230:231], off
	v_lshl_add_u64 v[230:231], s[28:29], 0, v[132:133]
	s_mov_b32 m0, s39
	s_nop 0
	global_load_lds_dwordx4 v[230:231], off
	s_waitcnt vmcnt(8)
	s_waitcnt lgkmcnt(0)
	s_barrier
	s_setprio 1
	v_mfma_f32_16x16x32_bf16 v[126:129], v[150:153], v[188:191], v[126:129]
	v_mfma_f32_16x16x32_bf16 v[122:125], v[158:161], v[188:191], v[122:125]
	v_mfma_f32_16x16x32_bf16 v[114:117], v[150:153], v[196:199], v[114:117]
	v_mfma_f32_16x16x32_bf16 v[106:109], v[158:161], v[196:199], v[106:109]
	v_mfma_f32_16x16x32_bf16 v[98:101], v[150:153], v[204:207], v[98:101]
	v_mfma_f32_16x16x32_bf16 v[90:93], v[158:161], v[204:207], v[90:93]
	v_mfma_f32_16x16x32_bf16 v[82:85], v[150:153], v[212:215], v[82:85]
	v_mfma_f32_16x16x32_bf16 v[74:77], v[158:161], v[212:215], v[74:77]
	v_mfma_f32_16x16x32_bf16 v[126:129], v[154:157], v[192:195], v[126:129]
	v_mfma_f32_16x16x32_bf16 v[122:125], v[162:165], v[192:195], v[122:125]
	v_mfma_f32_16x16x32_bf16 v[114:117], v[154:157], v[200:203], v[114:117]
	v_mfma_f32_16x16x32_bf16 v[106:109], v[162:165], v[200:203], v[106:109]
	v_mfma_f32_16x16x32_bf16 v[98:101], v[154:157], v[208:211], v[98:101]
	v_mfma_f32_16x16x32_bf16 v[90:93], v[162:165], v[208:211], v[90:93]
	v_mfma_f32_16x16x32_bf16 v[82:85], v[154:157], v[216:219], v[82:85]
	v_mfma_f32_16x16x32_bf16 v[74:77], v[162:165], v[216:219], v[74:77]
	v_mfma_f32_16x16x32_bf16 v[118:121], v[166:169], v[188:191], v[118:121]
	v_mfma_f32_16x16x32_bf16 v[110:113], v[180:183], v[188:191], v[110:113]
	v_mfma_f32_16x16x32_bf16 v[102:105], v[166:169], v[196:199], v[102:105]
	v_mfma_f32_16x16x32_bf16 v[94:97], v[180:183], v[196:199], v[94:97]
	v_mfma_f32_16x16x32_bf16 v[86:89], v[166:169], v[204:207], v[86:89]
	v_mfma_f32_16x16x32_bf16 v[78:81], v[180:183], v[204:207], v[78:81]
	v_mfma_f32_16x16x32_bf16 v[70:73], v[166:169], v[212:215], v[70:73]
	v_mfma_f32_16x16x32_bf16 v[66:69], v[180:183], v[212:215], v[66:69]
	v_mfma_f32_16x16x32_bf16 v[118:121], v[170:173], v[192:195], v[118:121]
	v_mfma_f32_16x16x32_bf16 v[110:113], v[184:187], v[192:195], v[110:113]
	v_mfma_f32_16x16x32_bf16 v[102:105], v[170:173], v[200:203], v[102:105]
	v_mfma_f32_16x16x32_bf16 v[94:97], v[184:187], v[200:203], v[94:97]
	v_mfma_f32_16x16x32_bf16 v[86:89], v[170:173], v[208:211], v[86:89]
	v_mfma_f32_16x16x32_bf16 v[78:81], v[184:187], v[208:211], v[78:81]
	v_mfma_f32_16x16x32_bf16 v[70:73], v[170:173], v[216:219], v[70:73]
	v_mfma_f32_16x16x32_bf16 v[66:69], v[184:187], v[216:219], v[66:69]
	s_setprio 0
	s_barrier
; #define PG8_STAGE(bufoff, gbase, voff) do { _Pragma("unroll") for (int _i = 0; _i < 2; ++_i) \
;         __builtin_amdgcn_global_load_lds((const unsigned*)((const char*)(gbase) + (voff)[_i]), (PG8_LAS unsigned*)(lds + (bufoff) + ldsw + _i * 8192), 16, 0, 0); } while (0)
; #define PG8_LDA(dst, b, h) do { _Pragma("unroll") for (int m = 0; m < 4; ++m) _Pragma("unroll") for (int k = 0; k < 2; ++k) dst[m][k] = *(const PG8_LAS bf16x8*)(lds + PG8_SA(b, h) + aoff + m * 2048 + k * 1024); } while (0)
; #define PG8_MMA(ai, bj, At, Bt) do { __builtin_amdgcn_s_setprio(1); _Pragma("unroll") for (int m = 0; m < 4; ++m) _Pragma("unroll") for (int n = 0; n < 2; ++n) _Pragma("unroll") for (int k = 0; k < 2; ++k) \
;         acc[ai][bj][m][n] = __builtin_amdgcn_mfma_f32_16x16x32_bf16(Bt[n][k], At[m][k], acc[ai][bj][m][n], 0, 0, 0); __builtin_amdgcn_s_setprio(0); } while (0)
; #define PG8_WAIT_V(n) asm volatile("s_waitcnt vmcnt(" #n ")" ::: "memory")
; #define PG8_WAIT_L(n) asm volatile("s_waitcnt lgkmcnt(" #n ")" ::: "memory")
; #define PG8_BAR __builtin_amdgcn_s_barrier()
; #define PG8_SCHED __builtin_amdgcn_sched_barrier(0)
; template <class Epi, class Sched, bool ALIGN_EPI = false, bool SP2 = false>
; __device__ __forceinline__ void gemm_phase(PG8_LAS unsigned char* lds, const Gemm g, const Sched& S, const Epi& E) {
;     ...
;             PG8_LDA(At, 1, 1); PG8_STAGE(PG8_SB(1, 0), b3, voffB); PG8_STAGE(PG8_SB(1, 1), b3 + hstep, voffB); PG8_STAGE(PG8_SA(1, 0), a3, voffA);
;             PG8_WAIT_V(8); PG8_WAIT_L(0); PG8_BAR; PG8_MMA(1, 0, At, B0); PG8_MMA(1, 1, At, B1); PG8_BAR; PG8_SCHED;
	s_add_i32 s28, s49, s35
	v_lshl_add_u64 v[146:147], v[146:147], 0, s[96:97]
	s_mov_b32 m0, s28
	ds_read_b128 v[188:191], v149 offset:49152
	ds_read_b128 v[192:195], v149 offset:50176
	ds_read_b128 v[196:199], v149 offset:51200
	ds_read_b128 v[200:203], v149 offset:52224
	ds_read_b128 v[204:207], v149 offset:53248
	ds_read_b128 v[208:211], v149 offset:54272
	ds_read_b128 v[212:215], v149 offset:55296
	ds_read_b128 v[216:219], v149 offset:56320
	global_load_lds_dwordx4 v[146:147], off
	s_add_i32 m0, s28, 0x2000
	s_add_u32 s26, s26, 0x40080
	v_lshl_add_u64 v[146:147], v[220:221], 0, s[96:97]
	s_addc_u32 s27, s27, 0
	s_add_i32 s28, s50, s35
	global_load_lds_dwordx4 v[146:147], off
	v_lshl_add_u64 v[146:147], s[26:27], 0, v[134:135]
	s_mov_b32 m0, s28
	s_nop 0
	global_load_lds_dwordx4 v[146:147], off
	v_lshl_add_u64 v[146:147], s[26:27], 0, v[130:131]
	s_add_i32 m0, s28, 0x2000
	s_nop 0
	global_load_lds_dwordx4 v[146:147], off
	v_lshl_add_u64 v[146:147], v[222:223], 0, s[96:97]
	s_mov_b32 m0, s42
	s_nop 0
	global_load_lds_dwordx4 v[146:147], off
	v_lshl_add_u64 v[146:147], v[228:229], 0, s[96:97]
	s_mov_b32 m0, s43
	s_nop 0
	global_load_lds_dwordx4 v[146:147], off
	s_waitcnt vmcnt(8)
	s_waitcnt lgkmcnt(0)
	s_barrier
	s_setprio 1
	v_mfma_f32_16x16x32_bf16 v[62:65], v[150:153], v[188:191], v[62:65]
	v_mfma_f32_16x16x32_bf16 v[58:61], v[158:161], v[188:191], v[58:61]
	v_mfma_f32_16x16x32_bf16 v[50:53], v[150:153], v[196:199], v[50:53]
	v_mfma_f32_16x16x32_bf16 v[42:45], v[158:161], v[196:199], v[42:45]
	v_mfma_f32_16x16x32_bf16 v[34:37], v[150:153], v[204:207], v[34:37]
	v_mfma_f32_16x16x32_bf16 v[26:29], v[158:161], v[204:207], v[26:29]
	v_mfma_f32_16x16x32_bf16 v[18:21], v[150:153], v[212:215], v[18:21]
	v_mfma_f32_16x16x32_bf16 v[10:13], v[158:161], v[212:215], v[10:13]
	v_mfma_f32_16x16x32_bf16 v[62:65], v[154:157], v[192:195], v[62:65]
	v_mfma_f32_16x16x32_bf16 v[58:61], v[162:165], v[192:195], v[58:61]
	v_mfma_f32_16x16x32_bf16 v[50:53], v[154:157], v[200:203], v[50:53]
	v_mfma_f32_16x16x32_bf16 v[42:45], v[162:165], v[200:203], v[42:45]
	v_mfma_f32_16x16x32_bf16 v[34:37], v[154:157], v[208:211], v[34:37]
	v_mfma_f32_16x16x32_bf16 v[26:29], v[162:165], v[208:211], v[26:29]
	v_mfma_f32_16x16x32_bf16 v[18:21], v[154:157], v[216:219], v[18:21]
	v_mfma_f32_16x16x32_bf16 v[10:13], v[162:165], v[216:219], v[10:13]
	v_mfma_f32_16x16x32_bf16 v[54:57], v[166:169], v[188:191], v[54:57]
	v_mfma_f32_16x16x32_bf16 v[46:49], v[180:183], v[188:191], v[46:49]
	v_mfma_f32_16x16x32_bf16 v[38:41], v[166:169], v[196:199], v[38:41]
	v_mfma_f32_16x16x32_bf16 v[30:33], v[180:183], v[196:199], v[30:33]
	v_mfma_f32_16x16x32_bf16 v[22:25], v[166:169], v[204:207], v[22:25]
	v_mfma_f32_16x16x32_bf16 v[14:17], v[180:183], v[204:207], v[14:17]
	v_mfma_f32_16x16x32_bf16 v[6:9], v[166:169], v[212:215], v[6:9]
	v_mfma_f32_16x16x32_bf16 v[2:5], v[180:183], v[212:215], v[2:5]
	v_mfma_f32_16x16x32_bf16 v[54:57], v[170:173], v[192:195], v[54:57]
	v_mfma_f32_16x16x32_bf16 v[46:49], v[184:187], v[192:195], v[46:49]
	v_mfma_f32_16x16x32_bf16 v[38:41], v[170:173], v[200:203], v[38:41]
	v_mfma_f32_16x16x32_bf16 v[30:33], v[184:187], v[200:203], v[30:33]
	v_mfma_f32_16x16x32_bf16 v[22:25], v[170:173], v[208:211], v[22:25]
	v_mfma_f32_16x16x32_bf16 v[14:17], v[184:187], v[208:211], v[14:17]
	v_mfma_f32_16x16x32_bf16 v[6:9], v[170:173], v[216:219], v[6:9]
	v_mfma_f32_16x16x32_bf16 v[2:5], v[184:187], v[216:219], v[2:5]
	s_setprio 0
	s_barrier
	s_add_i32 s48, s48, 2
	s_add_u32 s24, s24, 0x100
	s_addc_u32 s25, s25, 0
	s_add_u32 s46, s46, 0x100
	s_addc_u32 s47, s47, 0
	s_cmp_gt_u32 s48, 13
	s_cbranch_scc0 .LBB0_812
	s_and_b64 vcc, exec, s[14:15]
	s_cbranch_vccz .LBB0_815
	s_barrier

; #define PG8_STAGE(bufoff, gbase, voff) do { _Pragma("unroll") for (int _i = 0; _i < 2; ++_i) \
;         __builtin_amdgcn_global_load_lds((const unsigned*)((const char*)(gbase) + (voff)[_i]), (PG8_LAS unsigned*)(lds + (bufoff) + ldsw + _i * 8192), 16, 0, 0); } while (0)
; #define PG8_LDA(dst, b, h) do { _Pragma("unroll") for (int m = 0; m < 4; ++m) _Pragma("unroll") for (int k = 0; k < 2; ++k) dst[m][k] = *(const PG8_LAS bf16x8*)(lds + PG8_SA(b, h) + aoff + m * 2048 + k * 1024); } while (0)
; #define PG8_MMA(ai, bj, At, Bt) do { __builtin_amdgcn_s_setprio(1); _Pragma("unroll") for (int m = 0; m < 4; ++m) _Pragma("unroll") for (int n = 0; n < 2; ++n) _Pragma("unroll") for (int k = 0; k < 2; ++k) \
;         acc[ai][bj][m][n] = __builtin_amdgcn_mfma_f32_16x16x32_bf16(Bt[n][k], At[m][k], acc[ai][bj][m][n], 0, 0, 0); __builtin_amdgcn_s_setprio(0); } while (0)
; #define PG8_WAIT_V(n) asm volatile("s_waitcnt vmcnt(" #n ")" ::: "memory")
; #define PG8_WAIT_L(n) asm volatile("s_waitcnt lgkmcnt(" #n ")" ::: "memory")
; #define PG8_BAR __builtin_amdgcn_s_barrier()
; #define PG8_SCHED __builtin_amdgcn_sched_barrier(0)
; template <class Epi, class Sched, bool ALIGN_EPI = false, bool SP2 = false>
; __device__ __forceinline__ void gemm_phase(PG8_LAS unsigned char* lds, const Gemm g, const Sched& S, const Epi& E) {
;     ...
;             PG8_WAIT_V(8); PG8_WAIT_L(0); PG8_BAR; PG8_MMA(0, 0, At, B0); PG8_MMA(0, 1, At, B1); PG8_BAR; PG8_SCHED;
;             PG8_LDA(At, 0, 1); PG8_STAGE(PG8_SB(0, 0), b2, voffB); PG8_STAGE(PG8_SB(0, 1), b2 + hstep, voffB); PG8_STAGE(PG8_SA(0, 0), a2, voffA);
;             PG8_WAIT_V(8); PG8_WAIT_L(0); PG8_BAR; PG8_MMA(1, 0, At, B0); PG8_MMA(1, 1, At, B1); PG8_BAR; PG8_SCHED;
.Levout_noz:
	s_waitcnt vmcnt(8)
	s_waitcnt lgkmcnt(0)
	s_barrier
	s_setprio 1
	v_mfma_f32_16x16x32_bf16 v[158:161], v[66:69], v[162:165], v[158:161]
	v_mfma_f32_16x16x32_bf16 v[154:157], v[82:85], v[162:165], v[154:157]
	v_mfma_f32_16x16x32_bf16 v[142:145], v[66:69], v[188:191], v[142:145]
	v_mfma_f32_16x16x32_bf16 v[138:141], v[82:85], v[188:191], v[138:141]
	v_mfma_f32_16x16x32_bf16 v[114:117], v[66:69], v[196:199], v[114:117]
	v_mfma_f32_16x16x32_bf16 v[110:113], v[82:85], v[196:199], v[110:113]
	v_mfma_f32_16x16x32_bf16 v[90:93], v[66:69], v[210:213], v[90:93]
	v_mfma_f32_16x16x32_bf16 v[86:89], v[82:85], v[210:213], v[86:89]
	v_mfma_f32_16x16x32_bf16 v[158:161], v[70:73], v[166:169], v[158:161]
	v_mfma_f32_16x16x32_bf16 v[154:157], v[94:97], v[166:169], v[154:157]
	v_mfma_f32_16x16x32_bf16 v[142:145], v[70:73], v[192:195], v[142:145]
	v_mfma_f32_16x16x32_bf16 v[138:141], v[94:97], v[192:195], v[138:141]
	v_mfma_f32_16x16x32_bf16 v[114:117], v[70:73], v[206:209], v[114:117]
	v_mfma_f32_16x16x32_bf16 v[110:113], v[94:97], v[206:209], v[110:113]
	v_mfma_f32_16x16x32_bf16 v[90:93], v[70:73], v[214:217], v[90:93]
	v_mfma_f32_16x16x32_bf16 v[86:89], v[94:97], v[214:217], v[86:89]
	v_mfma_f32_16x16x32_bf16 v[150:153], v[106:109], v[162:165], v[150:153]
	v_mfma_f32_16x16x32_bf16 v[146:149], v[130:133], v[162:165], v[146:149]
	v_mfma_f32_16x16x32_bf16 v[126:129], v[106:109], v[188:191], v[126:129]
	v_mfma_f32_16x16x32_bf16 v[122:125], v[130:133], v[188:191], v[122:125]
	v_mfma_f32_16x16x32_bf16 v[102:105], v[106:109], v[196:199], v[102:105]
	v_mfma_f32_16x16x32_bf16 v[98:101], v[130:133], v[196:199], v[98:101]
	v_mfma_f32_16x16x32_bf16 v[78:81], v[106:109], v[210:213], v[78:81]
	v_mfma_f32_16x16x32_bf16 v[74:77], v[130:133], v[210:213], v[74:77]
	v_mfma_f32_16x16x32_bf16 v[150:153], v[118:121], v[166:169], v[150:153]
	v_mfma_f32_16x16x32_bf16 v[146:149], v[134:137], v[166:169], v[146:149]
	v_mfma_f32_16x16x32_bf16 v[126:129], v[118:121], v[192:195], v[126:129]
	v_mfma_f32_16x16x32_bf16 v[122:125], v[134:137], v[192:195], v[122:125]
	v_mfma_f32_16x16x32_bf16 v[102:105], v[118:121], v[206:209], v[102:105]
	v_mfma_f32_16x16x32_bf16 v[98:101], v[134:137], v[206:209], v[98:101]
	v_mfma_f32_16x16x32_bf16 v[78:81], v[118:121], v[214:217], v[78:81]
	v_mfma_f32_16x16x32_bf16 v[74:77], v[134:137], v[214:217], v[74:77]
	s_setprio 0
	s_barrier
	s_add_i32 s56, s56, s42
	v_lshl_add_u64 v[200:201], s[10:11], 0, v[180:181]
	s_mov_b32 m0, s56
	ds_read_b128 v[162:165], v204 offset:16384
	ds_read_b128 v[166:169], v204 offset:17408
	ds_read_b128 v[188:191], v204 offset:18432
	ds_read_b128 v[192:195], v204 offset:19456
	ds_read_b128 v[196:199], v204 offset:20480
	ds_read_b128 v[206:209], v204 offset:21504
	ds_read_b128 v[210:213], v204 offset:22528
	ds_read_b128 v[214:217], v204 offset:23552
	global_load_lds_dwordx4 v[200:201], off
	s_add_i32 m0, s56, 0x2000
	s_add_u32 s56, s10, 0x40000
	v_lshl_add_u64 v[218:219], s[10:11], 0, v[170:171]
	s_addc_u32 s57, s11, 0
	s_add_i32 s58, s58, s42
	global_load_lds_dwordx4 v[218:219], off
	v_lshl_add_u64 v[220:221], s[56:57], 0, v[180:181]
	s_mov_b32 m0, s58
	v_lshl_add_u64 v[222:223], s[36:37], 0, v[172:173]
	global_load_lds_dwordx4 v[220:221], off
	v_lshl_add_u64 v[220:221], s[56:57], 0, v[170:171]
	s_add_i32 m0, s58, 0x2000
	s_nop 0
	global_load_lds_dwordx4 v[220:221], off
	v_lshl_add_u64 v[220:221], s[36:37], 0, v[182:183]
	s_mov_b32 m0, s43
	s_nop 0
	global_load_lds_dwordx4 v[220:221], off
	s_mov_b32 m0, s44
	s_nop 0
	global_load_lds_dwordx4 v[222:223], off
	s_waitcnt vmcnt(8)
	s_waitcnt lgkmcnt(0)
	s_barrier
	s_setprio 1
	v_mfma_f32_16x16x32_bf16 v[62:65], v[66:69], v[162:165], v[62:65]
	v_mfma_f32_16x16x32_bf16 v[58:61], v[82:85], v[162:165], v[58:61]
	v_mfma_f32_16x16x32_bf16 v[46:49], v[66:69], v[188:191], v[46:49]
	v_mfma_f32_16x16x32_bf16 v[42:45], v[82:85], v[188:191], v[42:45]
	v_mfma_f32_16x16x32_bf16 v[30:33], v[66:69], v[196:199], v[30:33]
	v_mfma_f32_16x16x32_bf16 v[26:29], v[82:85], v[196:199], v[26:29]
	v_mfma_f32_16x16x32_bf16 v[14:17], v[66:69], v[210:213], v[14:17]
	v_mfma_f32_16x16x32_bf16 v[10:13], v[82:85], v[210:213], v[10:13]
	v_mfma_f32_16x16x32_bf16 v[62:65], v[70:73], v[166:169], v[62:65]
	v_mfma_f32_16x16x32_bf16 v[58:61], v[94:97], v[166:169], v[58:61]
	v_mfma_f32_16x16x32_bf16 v[46:49], v[70:73], v[192:195], v[46:49]
	v_mfma_f32_16x16x32_bf16 v[42:45], v[94:97], v[192:195], v[42:45]
	v_mfma_f32_16x16x32_bf16 v[30:33], v[70:73], v[206:209], v[30:33]
	v_mfma_f32_16x16x32_bf16 v[26:29], v[94:97], v[206:209], v[26:29]
	v_mfma_f32_16x16x32_bf16 v[14:17], v[70:73], v[214:217], v[14:17]
	v_mfma_f32_16x16x32_bf16 v[10:13], v[94:97], v[214:217], v[10:13]
	v_mfma_f32_16x16x32_bf16 v[54:57], v[106:109], v[162:165], v[54:57]
	v_mfma_f32_16x16x32_bf16 v[50:53], v[130:133], v[162:165], v[50:53]
	v_mfma_f32_16x16x32_bf16 v[38:41], v[106:109], v[188:191], v[38:41]
	v_mfma_f32_16x16x32_bf16 v[34:37], v[130:133], v[188:191], v[34:37]
	v_mfma_f32_16x16x32_bf16 v[22:25], v[106:109], v[196:199], v[22:25]
	v_mfma_f32_16x16x32_bf16 v[18:21], v[130:133], v[196:199], v[18:21]
	v_mfma_f32_16x16x32_bf16 v[6:9], v[106:109], v[210:213], v[6:9]
	v_mfma_f32_16x16x32_bf16 v[2:5], v[130:133], v[210:213], v[2:5]
	v_mfma_f32_16x16x32_bf16 v[54:57], v[118:121], v[166:169], v[54:57]
	v_mfma_f32_16x16x32_bf16 v[50:53], v[134:137], v[166:169], v[50:53]
	v_mfma_f32_16x16x32_bf16 v[38:41], v[118:121], v[192:195], v[38:41]
	v_mfma_f32_16x16x32_bf16 v[34:37], v[134:137], v[192:195], v[34:37]
	v_mfma_f32_16x16x32_bf16 v[22:25], v[118:121], v[206:209], v[22:25]
	v_mfma_f32_16x16x32_bf16 v[18:21], v[134:137], v[206:209], v[18:21]
	v_mfma_f32_16x16x32_bf16 v[6:9], v[118:121], v[214:217], v[6:9]
	v_mfma_f32_16x16x32_bf16 v[2:5], v[134:137], v[214:217], v[2:5]
	s_setprio 0
	s_barrier
; #define PG8_STAGE(bufoff, gbase, voff) do { _Pragma("unroll") for (int _i = 0; _i < 2; ++_i) \
;         __builtin_amdgcn_global_load_lds((const unsigned*)((const char*)(gbase) + (voff)[_i]), (PG8_LAS unsigned*)(lds + (bufoff) + ldsw + _i * 8192), 16, 0, 0); } while (0)
; #define PG8_LDA(dst, b, h) do { _Pragma("unroll") for (int m = 0; m < 4; ++m) _Pragma("unroll") for (int k = 0; k < 2; ++k) dst[m][k] = *(const PG8_LAS bf16x8*)(lds + PG8_SA(b, h) + aoff + m * 2048 + k * 1024); } while (0)
; #define PG8_LDB(dst, b, h) do { _Pragma("unroll") for (int n = 0; n < 2; ++n) _Pragma("unroll") for (int k = 0; k < 2; ++k) dst[n][k] = *(const PG8_LAS bf16x8*)(lds + PG8_SB(b, h) + boff + n * 2048 + k * 1024); } while (0)
; #define PG8_MMA(ai, bj, At, Bt) do { __builtin_amdgcn_s_setprio(1); _Pragma("unroll") for (int m = 0; m < 4; ++m) _Pragma("unroll") for (int n = 0; n < 2; ++n) _Pragma("unroll") for (int k = 0; k < 2; ++k) \
;         acc[ai][bj][m][n] = __builtin_amdgcn_mfma_f32_16x16x32_bf16(Bt[n][k], At[m][k], acc[ai][bj][m][n], 0, 0, 0); __builtin_amdgcn_s_setprio(0); } while (0)
; #define PG8_WAIT_V(n) asm volatile("s_waitcnt vmcnt(" #n ")" ::: "memory")
; #define PG8_WAIT_L(n) asm volatile("s_waitcnt lgkmcnt(" #n ")" ::: "memory")
; #define PG8_BAR __builtin_amdgcn_s_barrier()
; #define PG8_SCHED __builtin_amdgcn_sched_barrier(0)
; template <class Epi, class Sched, bool ALIGN_EPI = false, bool SP2 = false>
; __device__ __forceinline__ void gemm_phase(PG8_LAS unsigned char* lds, const Gemm g, const Sched& S, const Epi& E) {
;     ...
;             PG8_LDB(B0, 1, 0); PG8_LDB(B1, 1, 1); PG8_SCHED; PG8_LDA(At, 1, 0); PG8_STAGE(PG8_SA(0, 1), a2 + hstep, voffA);
;             PG8_WAIT_V(8); PG8_WAIT_L(0); PG8_BAR; PG8_MMA(0, 0, At, B0); PG8_MMA(0, 1, At, B1); PG8_BAR; PG8_SCHED;
	s_add_i32 s56, 0, 0x18000
	s_add_i32 s57, 0, 0x1c000
	v_add_u32_e32 v94, s56, v203
	v_add_u32_e32 v134, s57, v203
	ds_read_b128 v[66:69], v94
	ds_read_b128 v[70:73], v94 offset:1024
	ds_read_b128 v[82:85], v94 offset:2048
	ds_read_b128 v[94:97], v94 offset:3072
	ds_read_b128 v[106:109], v134
	ds_read_b128 v[118:121], v134 offset:1024
	ds_read_b128 v[130:133], v134 offset:2048
	ds_read_b128 v[134:137], v134 offset:3072
	s_add_u32 s36, s36, 0x40000
	s_addc_u32 s37, s37, 0
	s_mov_b32 m0, s45
	v_lshl_add_u64 v[228:229], s[36:37], 0, v[182:183]
	ds_read_b128 v[162:165], v204 offset:32768
	ds_read_b128 v[166:169], v204 offset:33792
	ds_read_b128 v[188:191], v204 offset:34816
	ds_read_b128 v[192:195], v204 offset:35840
	ds_read_b128 v[196:199], v204 offset:36864
	ds_read_b128 v[206:209], v204 offset:37888
	ds_read_b128 v[210:213], v204 offset:38912
	ds_read_b128 v[214:217], v204 offset:39936
	global_load_lds_dwordx4 v[228:229], off
	v_lshl_add_u64 v[228:229], s[36:37], 0, v[172:173]
	s_mov_b32 m0, s46
	s_nop 0
	global_load_lds_dwordx4 v[228:229], off
	s_waitcnt vmcnt(8)
	s_waitcnt lgkmcnt(0)
	s_barrier
	s_setprio 1
	v_mfma_f32_16x16x32_bf16 v[158:161], v[66:69], v[162:165], v[158:161]
	v_mfma_f32_16x16x32_bf16 v[154:157], v[82:85], v[162:165], v[154:157]
	v_mfma_f32_16x16x32_bf16 v[142:145], v[66:69], v[188:191], v[142:145]
	v_mfma_f32_16x16x32_bf16 v[138:141], v[82:85], v[188:191], v[138:141]
	v_mfma_f32_16x16x32_bf16 v[114:117], v[66:69], v[196:199], v[114:117]
	v_mfma_f32_16x16x32_bf16 v[110:113], v[82:85], v[196:199], v[110:113]
	v_mfma_f32_16x16x32_bf16 v[90:93], v[66:69], v[210:213], v[90:93]
	v_mfma_f32_16x16x32_bf16 v[86:89], v[82:85], v[210:213], v[86:89]
	v_mfma_f32_16x16x32_bf16 v[158:161], v[70:73], v[166:169], v[158:161]
	v_mfma_f32_16x16x32_bf16 v[154:157], v[94:97], v[166:169], v[154:157]
	v_mfma_f32_16x16x32_bf16 v[142:145], v[70:73], v[192:195], v[142:145]
	v_mfma_f32_16x16x32_bf16 v[138:141], v[94:97], v[192:195], v[138:141]
	v_mfma_f32_16x16x32_bf16 v[114:117], v[70:73], v[206:209], v[114:117]
	v_mfma_f32_16x16x32_bf16 v[110:113], v[94:97], v[206:209], v[110:113]
	v_mfma_f32_16x16x32_bf16 v[90:93], v[70:73], v[214:217], v[90:93]
	v_mfma_f32_16x16x32_bf16 v[86:89], v[94:97], v[214:217], v[86:89]
	v_mfma_f32_16x16x32_bf16 v[150:153], v[106:109], v[162:165], v[150:153]
	v_mfma_f32_16x16x32_bf16 v[146:149], v[130:133], v[162:165], v[146:149]
	v_mfma_f32_16x16x32_bf16 v[126:129], v[106:109], v[188:191], v[126:129]
	v_mfma_f32_16x16x32_bf16 v[122:125], v[130:133], v[188:191], v[122:125]
	v_mfma_f32_16x16x32_bf16 v[102:105], v[106:109], v[196:199], v[102:105]
	v_mfma_f32_16x16x32_bf16 v[98:101], v[130:133], v[196:199], v[98:101]
	v_mfma_f32_16x16x32_bf16 v[78:81], v[106:109], v[210:213], v[78:81]
	v_mfma_f32_16x16x32_bf16 v[74:77], v[130:133], v[210:213], v[74:77]
	v_mfma_f32_16x16x32_bf16 v[150:153], v[118:121], v[166:169], v[150:153]
	v_mfma_f32_16x16x32_bf16 v[146:149], v[134:137], v[166:169], v[146:149]
	v_mfma_f32_16x16x32_bf16 v[126:129], v[118:121], v[192:195], v[126:129]
	v_mfma_f32_16x16x32_bf16 v[122:125], v[134:137], v[192:195], v[122:125]
	v_mfma_f32_16x16x32_bf16 v[102:105], v[118:121], v[206:209], v[102:105]
	v_mfma_f32_16x16x32_bf16 v[98:101], v[134:137], v[206:209], v[98:101]
	v_mfma_f32_16x16x32_bf16 v[78:81], v[118:121], v[214:217], v[78:81]
	v_mfma_f32_16x16x32_bf16 v[74:77], v[134:137], v[214:217], v[74:77]
	s_setprio 0
	s_barrier
; #define PG8_STAGE(bufoff, gbase, voff) do { _Pragma("unroll") for (int _i = 0; _i < 2; ++_i) \
;         __builtin_amdgcn_global_load_lds((const unsigned*)((const char*)(gbase) + (voff)[_i]), (PG8_LAS unsigned*)(lds + (bufoff) + ldsw + _i * 8192), 16, 0, 0); } while (0)
; #define PG8_LDA(dst, b, h) do { _Pragma("unroll") for (int m = 0; m < 4; ++m) _Pragma("unroll") for (int k = 0; k < 2; ++k) dst[m][k] = *(const PG8_LAS bf16x8*)(lds + PG8_SA(b, h) + aoff + m * 2048 + k * 1024); } while (0)
; #define PG8_MMA(ai, bj, At, Bt) do { __builtin_amdgcn_s_setprio(1); _Pragma("unroll") for (int m = 0; m < 4; ++m) _Pragma("unroll") for (int n = 0; n < 2; ++n) _Pragma("unroll") for (int k = 0; k < 2; ++k) \
;         acc[ai][bj][m][n] = __builtin_amdgcn_mfma_f32_16x16x32_bf16(Bt[n][k], At[m][k], acc[ai][bj][m][n], 0, 0, 0); __builtin_amdgcn_s_setprio(0); } while (0)
; #define PG8_WAIT_V(n) asm volatile("s_waitcnt vmcnt(" #n ")" ::: "memory")
; #define PG8_WAIT_L(n) asm volatile("s_waitcnt lgkmcnt(" #n ")" ::: "memory")
; #define PG8_BAR __builtin_amdgcn_s_barrier()
; #define PG8_SCHED __builtin_amdgcn_sched_barrier(0)
; template <class Epi, class Sched, bool ALIGN_EPI = false, bool SP2 = false>
; __device__ __forceinline__ void gemm_phase(PG8_LAS unsigned char* lds, const Gemm g, const Sched& S, const Epi& E) {
;     ...
;         for (int t = 0; t < nt; t += 2) {
;             const bool last = (t == nt - 2);
;             const char* a1 = cA + (size_t)(t + 1) * kstep;
;             const char* a2 = last ? nA : cA + (size_t)(t + 2) * kstep; const char* b2 = last ? nB : cB + (size_t)(t + 2) * kstep;
;             const char* a3 = a2 + kstep; const char* b3 = b2 + kstep;
;     ...
;             PG8_LDA(At, 1, 1); PG8_STAGE(PG8_SB(1, 0), b3, voffB); PG8_STAGE(PG8_SB(1, 1), b3 + hstep, voffB); PG8_STAGE(PG8_SA(1, 0), a3, voffA);
;             PG8_WAIT_V(8); PG8_WAIT_L(0); PG8_BAR; PG8_MMA(1, 0, At, B0); PG8_MMA(1, 1, At, B1); PG8_BAR; PG8_SCHED;
	s_add_i32 s36, s56, s42
	v_lshl_add_u64 v[200:201], v[200:201], 0, s[96:97]
	s_mov_b32 m0, s36
	ds_read_b128 v[162:165], v204 offset:49152
	ds_read_b128 v[166:169], v204 offset:50176
	ds_read_b128 v[188:191], v204 offset:51200
	ds_read_b128 v[192:195], v204 offset:52224
	ds_read_b128 v[196:199], v204 offset:53248
	ds_read_b128 v[206:209], v204 offset:54272
	ds_read_b128 v[210:213], v204 offset:55296
	ds_read_b128 v[214:217], v204 offset:56320
	global_load_lds_dwordx4 v[200:201], off
	s_add_i32 m0, s36, 0x2000
	s_add_u32 s10, s10, 0x40080
	v_lshl_add_u64 v[200:201], v[218:219], 0, s[96:97]
	s_addc_u32 s11, s11, 0
	s_add_i32 s36, s57, s42
	global_load_lds_dwordx4 v[200:201], off
	v_lshl_add_u64 v[200:201], s[10:11], 0, v[180:181]
	s_mov_b32 m0, s36
	s_nop 0
	global_load_lds_dwordx4 v[200:201], off
	v_lshl_add_u64 v[200:201], s[10:11], 0, v[170:171]
	s_add_i32 m0, s36, 0x2000
	s_nop 0
	global_load_lds_dwordx4 v[200:201], off
	v_lshl_add_u64 v[200:201], v[220:221], 0, s[96:97]
	s_mov_b32 m0, s50
	s_nop 0
	global_load_lds_dwordx4 v[200:201], off
	v_lshl_add_u64 v[200:201], v[222:223], 0, s[96:97]
	s_mov_b32 m0, s51
	s_nop 0
	global_load_lds_dwordx4 v[200:201], off
	s_waitcnt vmcnt(8)
	s_waitcnt lgkmcnt(0)
	s_barrier
	s_setprio 1
	v_mfma_f32_16x16x32_bf16 v[62:65], v[66:69], v[162:165], v[62:65]
	v_mfma_f32_16x16x32_bf16 v[58:61], v[82:85], v[162:165], v[58:61]
	v_mfma_f32_16x16x32_bf16 v[46:49], v[66:69], v[188:191], v[46:49]
	v_mfma_f32_16x16x32_bf16 v[42:45], v[82:85], v[188:191], v[42:45]
	v_mfma_f32_16x16x32_bf16 v[30:33], v[66:69], v[196:199], v[30:33]
	v_mfma_f32_16x16x32_bf16 v[26:29], v[82:85], v[196:199], v[26:29]
	v_mfma_f32_16x16x32_bf16 v[14:17], v[66:69], v[210:213], v[14:17]
	v_mfma_f32_16x16x32_bf16 v[10:13], v[82:85], v[210:213], v[10:13]
	v_mfma_f32_16x16x32_bf16 v[62:65], v[70:73], v[166:169], v[62:65]
	v_mfma_f32_16x16x32_bf16 v[58:61], v[94:97], v[166:169], v[58:61]
	v_mfma_f32_16x16x32_bf16 v[46:49], v[70:73], v[192:195], v[46:49]
	v_mfma_f32_16x16x32_bf16 v[42:45], v[94:97], v[192:195], v[42:45]
	v_mfma_f32_16x16x32_bf16 v[30:33], v[70:73], v[206:209], v[30:33]
	v_mfma_f32_16x16x32_bf16 v[26:29], v[94:97], v[206:209], v[26:29]
	v_mfma_f32_16x16x32_bf16 v[14:17], v[70:73], v[214:217], v[14:17]
	v_mfma_f32_16x16x32_bf16 v[10:13], v[94:97], v[214:217], v[10:13]
	v_mfma_f32_16x16x32_bf16 v[54:57], v[106:109], v[162:165], v[54:57]
	v_mfma_f32_16x16x32_bf16 v[50:53], v[130:133], v[162:165], v[50:53]
	v_mfma_f32_16x16x32_bf16 v[38:41], v[106:109], v[188:191], v[38:41]
	v_mfma_f32_16x16x32_bf16 v[34:37], v[130:133], v[188:191], v[34:37]
	v_mfma_f32_16x16x32_bf16 v[22:25], v[106:109], v[196:199], v[22:25]
	v_mfma_f32_16x16x32_bf16 v[18:21], v[130:133], v[196:199], v[18:21]
	v_mfma_f32_16x16x32_bf16 v[6:9], v[106:109], v[210:213], v[6:9]
	v_mfma_f32_16x16x32_bf16 v[2:5], v[130:133], v[210:213], v[2:5]
	v_mfma_f32_16x16x32_bf16 v[54:57], v[118:121], v[166:169], v[54:57]
	v_mfma_f32_16x16x32_bf16 v[50:53], v[134:137], v[166:169], v[50:53]
	v_mfma_f32_16x16x32_bf16 v[38:41], v[118:121], v[192:195], v[38:41]
	v_mfma_f32_16x16x32_bf16 v[34:37], v[134:137], v[192:195], v[34:37]
	v_mfma_f32_16x16x32_bf16 v[22:25], v[118:121], v[206:209], v[22:25]
	v_mfma_f32_16x16x32_bf16 v[18:21], v[134:137], v[206:209], v[18:21]
	v_mfma_f32_16x16x32_bf16 v[6:9], v[118:121], v[214:217], v[6:9]
	v_mfma_f32_16x16x32_bf16 v[2:5], v[134:137], v[214:217], v[2:5]
	s_setprio 0
	s_barrier
	s_add_i32 s55, s55, 2
	s_add_u32 s8, s8, 0x100
	s_addc_u32 s9, s9, 0
	s_add_u32 s33, s33, 0x100
	s_addc_u32 s54, s54, 0
	s_cmp_gt_u32 s55, 13
	s_cbranch_scc0 .LBB0_1075
	s_and_b64 vcc, exec, s[20:21]
	s_cbranch_vccz .LBB0_1078
	s_barrier

; #define PG8_STAGE(bufoff, gbase, voff) do { _Pragma("unroll") for (int _i = 0; _i < 2; ++_i) \
;         __builtin_amdgcn_global_load_lds((const unsigned*)((const char*)(gbase) + (voff)[_i]), (PG8_LAS unsigned*)(lds + (bufoff) + ldsw + _i * 8192), 16, 0, 0); } while (0)
; #define PG8_LDA(dst, b, h) do { _Pragma("unroll") for (int m = 0; m < 4; ++m) _Pragma("unroll") for (int k = 0; k < 2; ++k) dst[m][k] = *(const PG8_LAS bf16x8*)(lds + PG8_SA(b, h) + aoff + m * 2048 + k * 1024); } while (0)
; #define PG8_MMA(ai, bj, At, Bt) do { __builtin_amdgcn_s_setprio(1); _Pragma("unroll") for (int m = 0; m < 4; ++m) _Pragma("unroll") for (int n = 0; n < 2; ++n) _Pragma("unroll") for (int k = 0; k < 2; ++k) \
;         acc[ai][bj][m][n] = __builtin_amdgcn_mfma_f32_16x16x32_bf16(Bt[n][k], At[m][k], acc[ai][bj][m][n], 0, 0, 0); __builtin_amdgcn_s_setprio(0); } while (0)
; #define PG8_WAIT_V(n) asm volatile("s_waitcnt vmcnt(" #n ")" ::: "memory")
; #define PG8_WAIT_L(n) asm volatile("s_waitcnt lgkmcnt(" #n ")" ::: "memory")
; #define PG8_BAR __builtin_amdgcn_s_barrier()
; #define PG8_SCHED __builtin_amdgcn_sched_barrier(0)
; template <class Epi, class Sched, bool ALIGN_EPI = false, bool SP2 = false>
; __device__ __forceinline__ void gemm_phase(PG8_LAS unsigned char* lds, const Gemm g, const Sched& S, const Epi& E) {
;     ...
;             PG8_WAIT_V(8); PG8_WAIT_L(0); PG8_BAR; PG8_MMA(0, 0, At, B0); PG8_MMA(0, 1, At, B1); PG8_BAR; PG8_SCHED;
;             PG8_LDA(At, 0, 1); PG8_STAGE(PG8_SB(0, 0), b2, voffB); PG8_STAGE(PG8_SB(0, 1), b2 + hstep, voffB); PG8_STAGE(PG8_SA(0, 0), a2, voffA);
.Lffin_noz:
	s_waitcnt vmcnt(8)
	s_waitcnt lgkmcnt(0)
	s_barrier
	s_setprio 1
	v_mfma_f32_16x16x32_bf16 v[158:161], v[106:109], v[162:165], v[158:161]
	v_mfma_f32_16x16x32_bf16 v[154:157], v[114:117], v[162:165], v[154:157]
	v_mfma_f32_16x16x32_bf16 v[142:145], v[106:109], v[170:173], v[142:145]
	v_mfma_f32_16x16x32_bf16 v[138:141], v[114:117], v[170:173], v[138:141]
	v_mfma_f32_16x16x32_bf16 v[94:97], v[106:109], v[196:199], v[94:97]
	v_mfma_f32_16x16x32_bf16 v[90:93], v[114:117], v[196:199], v[90:93]
	v_mfma_f32_16x16x32_bf16 v[78:81], v[106:109], v[204:207], v[78:81]
	v_mfma_f32_16x16x32_bf16 v[74:77], v[114:117], v[204:207], v[74:77]
	v_mfma_f32_16x16x32_bf16 v[158:161], v[110:113], v[166:169], v[158:161]
	v_mfma_f32_16x16x32_bf16 v[154:157], v[118:121], v[166:169], v[154:157]
	v_mfma_f32_16x16x32_bf16 v[142:145], v[110:113], v[192:195], v[142:145]
	v_mfma_f32_16x16x32_bf16 v[138:141], v[118:121], v[192:195], v[138:141]
	v_mfma_f32_16x16x32_bf16 v[94:97], v[110:113], v[200:203], v[94:97]
	v_mfma_f32_16x16x32_bf16 v[90:93], v[118:121], v[200:203], v[90:93]
	v_mfma_f32_16x16x32_bf16 v[78:81], v[110:113], v[208:211], v[78:81]
	v_mfma_f32_16x16x32_bf16 v[74:77], v[118:121], v[208:211], v[74:77]
	v_mfma_f32_16x16x32_bf16 v[150:153], v[122:125], v[162:165], v[150:153]
	v_mfma_f32_16x16x32_bf16 v[146:149], v[130:133], v[162:165], v[146:149]
	v_mfma_f32_16x16x32_bf16 v[102:105], v[122:125], v[170:173], v[102:105]
	v_mfma_f32_16x16x32_bf16 v[98:101], v[130:133], v[170:173], v[98:101]
	v_mfma_f32_16x16x32_bf16 v[86:89], v[122:125], v[196:199], v[86:89]
	v_mfma_f32_16x16x32_bf16 v[82:85], v[130:133], v[196:199], v[82:85]
	v_mfma_f32_16x16x32_bf16 v[70:73], v[122:125], v[204:207], v[70:73]
	v_mfma_f32_16x16x32_bf16 v[66:69], v[130:133], v[204:207], v[66:69]
	v_mfma_f32_16x16x32_bf16 v[150:153], v[126:129], v[166:169], v[150:153]
	v_mfma_f32_16x16x32_bf16 v[146:149], v[134:137], v[166:169], v[146:149]
	v_mfma_f32_16x16x32_bf16 v[102:105], v[126:129], v[192:195], v[102:105]
	v_mfma_f32_16x16x32_bf16 v[98:101], v[134:137], v[192:195], v[98:101]
	v_mfma_f32_16x16x32_bf16 v[86:89], v[126:129], v[200:203], v[86:89]
	v_mfma_f32_16x16x32_bf16 v[82:85], v[134:137], v[200:203], v[82:85]
	v_mfma_f32_16x16x32_bf16 v[70:73], v[126:129], v[208:211], v[70:73]
	v_mfma_f32_16x16x32_bf16 v[66:69], v[134:137], v[208:211], v[66:69]
	s_setprio 0
	s_barrier
	s_add_i32 s69, s69, s52
	v_lshl_add_u64 v[212:213], s[44:45], 0, v[184:185]
	s_mov_b32 m0, s69
	ds_read_b128 v[162:165], v230 offset:16384
	ds_read_b128 v[166:169], v230 offset:17408
	ds_read_b128 v[170:173], v230 offset:18432
	ds_read_b128 v[192:195], v230 offset:19456
	ds_read_b128 v[196:199], v230 offset:20480
	ds_read_b128 v[200:203], v230 offset:21504
	ds_read_b128 v[204:207], v230 offset:22528
	ds_read_b128 v[208:211], v230 offset:23552
	global_load_lds_dwordx4 v[212:213], off
	s_add_i32 m0, s69, 0x2000
	s_add_u32 s70, s44, 0x40000
	v_lshl_add_u64 v[214:215], s[44:45], 0, v[180:181]
	s_addc_u32 s71, s45, 0
	s_add_i32 s69, s72, s52
	global_load_lds_dwordx4 v[214:215], off
	v_lshl_add_u64 v[216:217], s[70:71], 0, v[184:185]
	s_mov_b32 m0, s69
	v_lshl_add_u64 v[218:219], s[46:47], 0, v[182:183]
	global_load_lds_dwordx4 v[216:217], off
	v_lshl_add_u64 v[216:217], s[70:71], 0, v[180:181]
	s_add_i32 m0, s69, 0x2000
	s_nop 0
	global_load_lds_dwordx4 v[216:217], off
	v_lshl_add_u64 v[216:217], s[46:47], 0, v[186:187]
	s_mov_b32 m0, s53
	s_nop 0
	global_load_lds_dwordx4 v[216:217], off
	s_mov_b32 m0, s54
	s_nop 0
	global_load_lds_dwordx4 v[218:219], off
	s_cmp_lg_u32 s68, -2
	s_cbranch_scc1 .Lffin_w8
	s_cmp_lt_u32 s57, 2
	s_cbranch_scc1 .Lffin_w8
	s_waitcnt vmcnt(16)
	s_branch .Lffin_wd

; #define PG8_STAGE(bufoff, gbase, voff) do { _Pragma("unroll") for (int _i = 0; _i < 2; ++_i) \
;         __builtin_amdgcn_global_load_lds((const unsigned*)((const char*)(gbase) + (voff)[_i]), (PG8_LAS unsigned*)(lds + (bufoff) + ldsw + _i * 8192), 16, 0, 0); } while (0)
; #define PG8_LDA(dst, b, h) do { _Pragma("unroll") for (int m = 0; m < 4; ++m) _Pragma("unroll") for (int k = 0; k < 2; ++k) dst[m][k] = *(const PG8_LAS bf16x8*)(lds + PG8_SA(b, h) + aoff + m * 2048 + k * 1024); } while (0)
; #define PG8_LDB(dst, b, h) do { _Pragma("unroll") for (int n = 0; n < 2; ++n) _Pragma("unroll") for (int k = 0; k < 2; ++k) dst[n][k] = *(const PG8_LAS bf16x8*)(lds + PG8_SB(b, h) + boff + n * 2048 + k * 1024); } while (0)
; #define PG8_MMA(ai, bj, At, Bt) do { __builtin_amdgcn_s_setprio(1); _Pragma("unroll") for (int m = 0; m < 4; ++m) _Pragma("unroll") for (int n = 0; n < 2; ++n) _Pragma("unroll") for (int k = 0; k < 2; ++k) \
;         acc[ai][bj][m][n] = __builtin_amdgcn_mfma_f32_16x16x32_bf16(Bt[n][k], At[m][k], acc[ai][bj][m][n], 0, 0, 0); __builtin_amdgcn_s_setprio(0); } while (0)
; #define PG8_WAIT_V(n) asm volatile("s_waitcnt vmcnt(" #n ")" ::: "memory")
; #define PG8_WAIT_L(n) asm volatile("s_waitcnt lgkmcnt(" #n ")" ::: "memory")
; #define PG8_BAR __builtin_amdgcn_s_barrier()
; #define PG8_SCHED __builtin_amdgcn_sched_barrier(0)
; template <class Epi, class Sched, bool ALIGN_EPI = false, bool SP2 = false>
; __device__ __forceinline__ void gemm_phase(PG8_LAS unsigned char* lds, const Gemm g, const Sched& S, const Epi& E) {
;     ...
;             PG8_WAIT_V(8); PG8_WAIT_L(0); PG8_BAR; PG8_MMA(1, 0, At, B0); PG8_MMA(1, 1, At, B1); PG8_BAR; PG8_SCHED;
;             PG8_LDB(B0, 1, 0); PG8_LDB(B1, 1, 1); PG8_SCHED; PG8_LDA(At, 1, 0); PG8_STAGE(PG8_SA(0, 1), a2 + hstep, voffA);
;             PG8_WAIT_V(8); PG8_WAIT_L(0); PG8_BAR; PG8_MMA(0, 0, At, B0); PG8_MMA(0, 1, At, B1); PG8_BAR; PG8_SCHED;
.Lffin_wd:
	s_waitcnt lgkmcnt(0)
	s_barrier
	s_setprio 1
	v_mfma_f32_16x16x32_bf16 v[62:65], v[106:109], v[162:165], v[62:65]
	v_mfma_f32_16x16x32_bf16 v[58:61], v[114:117], v[162:165], v[58:61]
	v_mfma_f32_16x16x32_bf16 v[46:49], v[106:109], v[170:173], v[46:49]
	v_mfma_f32_16x16x32_bf16 v[42:45], v[114:117], v[170:173], v[42:45]
	v_mfma_f32_16x16x32_bf16 v[30:33], v[106:109], v[196:199], v[30:33]
	v_mfma_f32_16x16x32_bf16 v[26:29], v[114:117], v[196:199], v[26:29]
	v_mfma_f32_16x16x32_bf16 v[14:17], v[106:109], v[204:207], v[14:17]
	v_mfma_f32_16x16x32_bf16 v[10:13], v[114:117], v[204:207], v[10:13]
	v_mfma_f32_16x16x32_bf16 v[62:65], v[110:113], v[166:169], v[62:65]
	v_mfma_f32_16x16x32_bf16 v[58:61], v[118:121], v[166:169], v[58:61]
	v_mfma_f32_16x16x32_bf16 v[46:49], v[110:113], v[192:195], v[46:49]
	v_mfma_f32_16x16x32_bf16 v[42:45], v[118:121], v[192:195], v[42:45]
	v_mfma_f32_16x16x32_bf16 v[30:33], v[110:113], v[200:203], v[30:33]
	v_mfma_f32_16x16x32_bf16 v[26:29], v[118:121], v[200:203], v[26:29]
	v_mfma_f32_16x16x32_bf16 v[14:17], v[110:113], v[208:211], v[14:17]
	v_mfma_f32_16x16x32_bf16 v[10:13], v[118:121], v[208:211], v[10:13]
	v_mfma_f32_16x16x32_bf16 v[54:57], v[122:125], v[162:165], v[54:57]
	v_mfma_f32_16x16x32_bf16 v[50:53], v[130:133], v[162:165], v[50:53]
	v_mfma_f32_16x16x32_bf16 v[38:41], v[122:125], v[170:173], v[38:41]
	v_mfma_f32_16x16x32_bf16 v[34:37], v[130:133], v[170:173], v[34:37]
	v_mfma_f32_16x16x32_bf16 v[22:25], v[122:125], v[196:199], v[22:25]
	v_mfma_f32_16x16x32_bf16 v[18:21], v[130:133], v[196:199], v[18:21]
	v_mfma_f32_16x16x32_bf16 v[6:9], v[122:125], v[204:207], v[6:9]
	v_mfma_f32_16x16x32_bf16 v[2:5], v[130:133], v[204:207], v[2:5]
	v_mfma_f32_16x16x32_bf16 v[54:57], v[126:129], v[166:169], v[54:57]
	v_mfma_f32_16x16x32_bf16 v[50:53], v[134:137], v[166:169], v[50:53]
	v_mfma_f32_16x16x32_bf16 v[38:41], v[126:129], v[192:195], v[38:41]
	v_mfma_f32_16x16x32_bf16 v[34:37], v[134:137], v[192:195], v[34:37]
	v_mfma_f32_16x16x32_bf16 v[22:25], v[126:129], v[200:203], v[22:25]
	v_mfma_f32_16x16x32_bf16 v[18:21], v[134:137], v[200:203], v[18:21]
	v_mfma_f32_16x16x32_bf16 v[6:9], v[126:129], v[208:211], v[6:9]
	v_mfma_f32_16x16x32_bf16 v[2:5], v[134:137], v[208:211], v[2:5]
	s_setprio 0
	s_barrier
	s_add_i32 s69, 0, 0x18000
	s_add_i32 s70, 0, 0x1c000
	v_add_u32_e32 v118, s69, v229
	v_add_u32_e32 v134, s70, v229
	ds_read_b128 v[106:109], v118
	ds_read_b128 v[110:113], v118 offset:1024
	ds_read_b128 v[114:117], v118 offset:2048
	ds_read_b128 v[118:121], v118 offset:3072
	ds_read_b128 v[122:125], v134
	ds_read_b128 v[126:129], v134 offset:1024
	ds_read_b128 v[130:133], v134 offset:2048
	ds_read_b128 v[134:137], v134 offset:3072
	s_add_u32 s46, s46, 0x40000
	s_addc_u32 s47, s47, 0
	s_mov_b32 m0, s55
	v_lshl_add_u64 v[220:221], s[46:47], 0, v[186:187]
	ds_read_b128 v[162:165], v230 offset:32768
	ds_read_b128 v[166:169], v230 offset:33792
	ds_read_b128 v[170:173], v230 offset:34816
	ds_read_b128 v[192:195], v230 offset:35840
	ds_read_b128 v[196:199], v230 offset:36864
	ds_read_b128 v[200:203], v230 offset:37888
	ds_read_b128 v[204:207], v230 offset:38912
	ds_read_b128 v[208:211], v230 offset:39936
	global_load_lds_dwordx4 v[220:221], off
	v_lshl_add_u64 v[220:221], s[46:47], 0, v[182:183]
	s_mov_b32 m0, s56
	s_nop 0
	global_load_lds_dwordx4 v[220:221], off
	s_waitcnt vmcnt(8)
	s_waitcnt lgkmcnt(0)
	s_barrier
	s_setprio 1
	v_mfma_f32_16x16x32_bf16 v[158:161], v[106:109], v[162:165], v[158:161]
	v_mfma_f32_16x16x32_bf16 v[154:157], v[114:117], v[162:165], v[154:157]
	v_mfma_f32_16x16x32_bf16 v[142:145], v[106:109], v[170:173], v[142:145]
	v_mfma_f32_16x16x32_bf16 v[138:141], v[114:117], v[170:173], v[138:141]
	v_mfma_f32_16x16x32_bf16 v[94:97], v[106:109], v[196:199], v[94:97]
	v_mfma_f32_16x16x32_bf16 v[90:93], v[114:117], v[196:199], v[90:93]
	v_mfma_f32_16x16x32_bf16 v[78:81], v[106:109], v[204:207], v[78:81]
	v_mfma_f32_16x16x32_bf16 v[74:77], v[114:117], v[204:207], v[74:77]
	v_mfma_f32_16x16x32_bf16 v[158:161], v[110:113], v[166:169], v[158:161]
	v_mfma_f32_16x16x32_bf16 v[154:157], v[118:121], v[166:169], v[154:157]
	v_mfma_f32_16x16x32_bf16 v[142:145], v[110:113], v[192:195], v[142:145]
	v_mfma_f32_16x16x32_bf16 v[138:141], v[118:121], v[192:195], v[138:141]
	v_mfma_f32_16x16x32_bf16 v[94:97], v[110:113], v[200:203], v[94:97]
	v_mfma_f32_16x16x32_bf16 v[90:93], v[118:121], v[200:203], v[90:93]
	v_mfma_f32_16x16x32_bf16 v[78:81], v[110:113], v[208:211], v[78:81]
	v_mfma_f32_16x16x32_bf16 v[74:77], v[118:121], v[208:211], v[74:77]
	v_mfma_f32_16x16x32_bf16 v[150:153], v[122:125], v[162:165], v[150:153]
	v_mfma_f32_16x16x32_bf16 v[146:149], v[130:133], v[162:165], v[146:149]
	v_mfma_f32_16x16x32_bf16 v[102:105], v[122:125], v[170:173], v[102:105]
	v_mfma_f32_16x16x32_bf16 v[98:101], v[130:133], v[170:173], v[98:101]
	v_mfma_f32_16x16x32_bf16 v[86:89], v[122:125], v[196:199], v[86:89]
	v_mfma_f32_16x16x32_bf16 v[82:85], v[130:133], v[196:199], v[82:85]
	v_mfma_f32_16x16x32_bf16 v[70:73], v[122:125], v[204:207], v[70:73]
	v_mfma_f32_16x16x32_bf16 v[66:69], v[130:133], v[204:207], v[66:69]
	v_mfma_f32_16x16x32_bf16 v[150:153], v[126:129], v[166:169], v[150:153]
	v_mfma_f32_16x16x32_bf16 v[146:149], v[134:137], v[166:169], v[146:149]
	v_mfma_f32_16x16x32_bf16 v[102:105], v[126:129], v[192:195], v[102:105]
	v_mfma_f32_16x16x32_bf16 v[98:101], v[134:137], v[192:195], v[98:101]
	v_mfma_f32_16x16x32_bf16 v[86:89], v[126:129], v[200:203], v[86:89]
	v_mfma_f32_16x16x32_bf16 v[82:85], v[134:137], v[200:203], v[82:85]
	v_mfma_f32_16x16x32_bf16 v[70:73], v[126:129], v[208:211], v[70:73]
	v_mfma_f32_16x16x32_bf16 v[66:69], v[134:137], v[208:211], v[66:69]
	s_setprio 0
	s_barrier
; #define PG8_STAGE(bufoff, gbase, voff) do { _Pragma("unroll") for (int _i = 0; _i < 2; ++_i) \
;         __builtin_amdgcn_global_load_lds((const unsigned*)((const char*)(gbase) + (voff)[_i]), (PG8_LAS unsigned*)(lds + (bufoff) + ldsw + _i * 8192), 16, 0, 0); } while (0)
; #define PG8_LDA(dst, b, h) do { _Pragma("unroll") for (int m = 0; m < 4; ++m) _Pragma("unroll") for (int k = 0; k < 2; ++k) dst[m][k] = *(const PG8_LAS bf16x8*)(lds + PG8_SA(b, h) + aoff + m * 2048 + k * 1024); } while (0)
; #define PG8_MMA(ai, bj, At, Bt) do { __builtin_amdgcn_s_setprio(1); _Pragma("unroll") for (int m = 0; m < 4; ++m) _Pragma("unroll") for (int n = 0; n < 2; ++n) _Pragma("unroll") for (int k = 0; k < 2; ++k) \
;         acc[ai][bj][m][n] = __builtin_amdgcn_mfma_f32_16x16x32_bf16(Bt[n][k], At[m][k], acc[ai][bj][m][n], 0, 0, 0); __builtin_amdgcn_s_setprio(0); } while (0)
; #define PG8_WAIT_V(n) asm volatile("s_waitcnt vmcnt(" #n ")" ::: "memory")
; #define PG8_WAIT_L(n) asm volatile("s_waitcnt lgkmcnt(" #n ")" ::: "memory")
; #define PG8_BAR __builtin_amdgcn_s_barrier()
; #define PG8_SCHED __builtin_amdgcn_sched_barrier(0)
; template <class Epi, class Sched, bool ALIGN_EPI = false, bool SP2 = false>
; __device__ __forceinline__ void gemm_phase(PG8_LAS unsigned char* lds, const Gemm g, const Sched& S, const Epi& E) {
;     ...
;         for (int t = 0; t < nt; t += 2) {
;             const bool last = (t == nt - 2);
;             const char* a1 = cA + (size_t)(t + 1) * kstep;
;             const char* a2 = last ? nA : cA + (size_t)(t + 2) * kstep; const char* b2 = last ? nB : cB + (size_t)(t + 2) * kstep;
;             const char* a3 = a2 + kstep; const char* b3 = b2 + kstep;
;     ...
;             PG8_LDA(At, 1, 1); PG8_STAGE(PG8_SB(1, 0), b3, voffB); PG8_STAGE(PG8_SB(1, 1), b3 + hstep, voffB); PG8_STAGE(PG8_SA(1, 0), a3, voffA);
;             PG8_WAIT_V(8); PG8_WAIT_L(0); PG8_BAR; PG8_MMA(1, 0, At, B0); PG8_MMA(1, 1, At, B1); PG8_BAR; PG8_SCHED;
	s_add_i32 s46, s69, s52
	v_lshl_add_u64 v[212:213], v[212:213], 0, s[96:97]
	s_mov_b32 m0, s46
	ds_read_b128 v[162:165], v230 offset:49152
	ds_read_b128 v[166:169], v230 offset:50176
	ds_read_b128 v[170:173], v230 offset:51200
	ds_read_b128 v[192:195], v230 offset:52224
	ds_read_b128 v[196:199], v230 offset:53248
	ds_read_b128 v[200:203], v230 offset:54272
	ds_read_b128 v[204:207], v230 offset:55296
	ds_read_b128 v[208:211], v230 offset:56320
	global_load_lds_dwordx4 v[212:213], off
	s_add_i32 m0, s46, 0x2000
	s_add_u32 s44, s44, 0x40080
	v_lshl_add_u64 v[212:213], v[214:215], 0, s[96:97]
	s_addc_u32 s45, s45, 0
	s_add_i32 s46, s70, s52
	global_load_lds_dwordx4 v[212:213], off
	v_lshl_add_u64 v[212:213], s[44:45], 0, v[184:185]
	s_mov_b32 m0, s46
	s_nop 0
	global_load_lds_dwordx4 v[212:213], off
	v_lshl_add_u64 v[212:213], s[44:45], 0, v[180:181]
	s_add_i32 m0, s46, 0x2000
	s_nop 0
	global_load_lds_dwordx4 v[212:213], off
	v_lshl_add_u64 v[212:213], v[216:217], 0, s[96:97]
	s_mov_b32 m0, s60
	s_nop 0
	global_load_lds_dwordx4 v[212:213], off
	v_lshl_add_u64 v[212:213], v[218:219], 0, s[96:97]
	s_mov_b32 m0, s61
	s_nop 0
	global_load_lds_dwordx4 v[212:213], off
	s_waitcnt vmcnt(8)
	s_waitcnt lgkmcnt(0)
	s_barrier
	s_setprio 1
	v_mfma_f32_16x16x32_bf16 v[62:65], v[106:109], v[162:165], v[62:65]
	v_mfma_f32_16x16x32_bf16 v[58:61], v[114:117], v[162:165], v[58:61]
	v_mfma_f32_16x16x32_bf16 v[46:49], v[106:109], v[170:173], v[46:49]
	v_mfma_f32_16x16x32_bf16 v[42:45], v[114:117], v[170:173], v[42:45]
	v_mfma_f32_16x16x32_bf16 v[30:33], v[106:109], v[196:199], v[30:33]
	v_mfma_f32_16x16x32_bf16 v[26:29], v[114:117], v[196:199], v[26:29]
	v_mfma_f32_16x16x32_bf16 v[14:17], v[106:109], v[204:207], v[14:17]
	v_mfma_f32_16x16x32_bf16 v[10:13], v[114:117], v[204:207], v[10:13]
	v_mfma_f32_16x16x32_bf16 v[62:65], v[110:113], v[166:169], v[62:65]
	v_mfma_f32_16x16x32_bf16 v[58:61], v[118:121], v[166:169], v[58:61]
	v_mfma_f32_16x16x32_bf16 v[46:49], v[110:113], v[192:195], v[46:49]
	v_mfma_f32_16x16x32_bf16 v[42:45], v[118:121], v[192:195], v[42:45]
	v_mfma_f32_16x16x32_bf16 v[30:33], v[110:113], v[200:203], v[30:33]
	v_mfma_f32_16x16x32_bf16 v[26:29], v[118:121], v[200:203], v[26:29]
	v_mfma_f32_16x16x32_bf16 v[14:17], v[110:113], v[208:211], v[14:17]
	v_mfma_f32_16x16x32_bf16 v[10:13], v[118:121], v[208:211], v[10:13]
	v_mfma_f32_16x16x32_bf16 v[54:57], v[122:125], v[162:165], v[54:57]
	v_mfma_f32_16x16x32_bf16 v[50:53], v[130:133], v[162:165], v[50:53]
	v_mfma_f32_16x16x32_bf16 v[38:41], v[122:125], v[170:173], v[38:41]
	v_mfma_f32_16x16x32_bf16 v[34:37], v[130:133], v[170:173], v[34:37]
	v_mfma_f32_16x16x32_bf16 v[22:25], v[122:125], v[196:199], v[22:25]
	v_mfma_f32_16x16x32_bf16 v[18:21], v[130:133], v[196:199], v[18:21]
	v_mfma_f32_16x16x32_bf16 v[6:9], v[122:125], v[204:207], v[6:9]
	v_mfma_f32_16x16x32_bf16 v[2:5], v[130:133], v[204:207], v[2:5]
	v_mfma_f32_16x16x32_bf16 v[54:57], v[126:129], v[166:169], v[54:57]
	v_mfma_f32_16x16x32_bf16 v[50:53], v[134:137], v[166:169], v[50:53]
	v_mfma_f32_16x16x32_bf16 v[38:41], v[126:129], v[192:195], v[38:41]
	v_mfma_f32_16x16x32_bf16 v[34:37], v[134:137], v[192:195], v[34:37]
	v_mfma_f32_16x16x32_bf16 v[22:25], v[126:129], v[200:203], v[22:25]
	v_mfma_f32_16x16x32_bf16 v[18:21], v[134:137], v[200:203], v[18:21]
	v_mfma_f32_16x16x32_bf16 v[6:9], v[126:129], v[208:211], v[6:9]
	v_mfma_f32_16x16x32_bf16 v[2:5], v[134:137], v[208:211], v[2:5]
	s_setprio 0
	s_barrier
	s_add_i32 s68, s68, 2
	s_add_u32 s8, s8, 0x100
	s_addc_u32 s9, s9, 0
	s_add_u32 s66, s66, 0x100
	s_addc_u32 s67, s67, 0
	s_cmp_gt_u32 s68, 13
	s_cbranch_scc0 .LBB0_1247
	s_and_b64 vcc, exec, s[24:25]
	s_cbranch_vccz .LBB0_1250
	s_barrier

; #define PG8_STAGE(bufoff, gbase, voff) do { _Pragma("unroll") for (int _i = 0; _i < 2; ++_i) \
;         __builtin_amdgcn_global_load_lds((const unsigned*)((const char*)(gbase) + (voff)[_i]), (PG8_LAS unsigned*)(lds + (bufoff) + ldsw + _i * 8192), 16, 0, 0); } while (0)
; #define PG8_LDA(dst, b, h) do { _Pragma("unroll") for (int m = 0; m < 4; ++m) _Pragma("unroll") for (int k = 0; k < 2; ++k) dst[m][k] = *(const PG8_LAS bf16x8*)(lds + PG8_SA(b, h) + aoff + m * 2048 + k * 1024); } while (0)
; #define PG8_MMA(ai, bj, At, Bt) do { __builtin_amdgcn_s_setprio(1); _Pragma("unroll") for (int m = 0; m < 4; ++m) _Pragma("unroll") for (int n = 0; n < 2; ++n) _Pragma("unroll") for (int k = 0; k < 2; ++k) \
;         acc[ai][bj][m][n] = __builtin_amdgcn_mfma_f32_16x16x32_bf16(Bt[n][k], At[m][k], acc[ai][bj][m][n], 0, 0, 0); __builtin_amdgcn_s_setprio(0); } while (0)
; #define PG8_WAIT_V(n) asm volatile("s_waitcnt vmcnt(" #n ")" ::: "memory")
; #define PG8_WAIT_L(n) asm volatile("s_waitcnt lgkmcnt(" #n ")" ::: "memory")
; #define PG8_BAR __builtin_amdgcn_s_barrier()
; #define PG8_SCHED __builtin_amdgcn_sched_barrier(0)
; template <class Epi, class Sched, bool ALIGN_EPI = false, bool SP2 = false>
; __device__ __forceinline__ void gemm_phase(PG8_LAS unsigned char* lds, const Gemm g, const Sched& S, const Epi& E) {
;     ...
;             PG8_WAIT_V(8); PG8_WAIT_L(0); PG8_BAR; PG8_MMA(0, 0, At, B0); PG8_MMA(0, 1, At, B1); PG8_BAR; PG8_SCHED;
;             PG8_LDA(At, 0, 1); PG8_STAGE(PG8_SB(0, 0), b2, voffB); PG8_STAGE(PG8_SB(0, 1), b2 + hstep, voffB); PG8_STAGE(PG8_SA(0, 0), a2, voffA);
;             PG8_WAIT_V(8); PG8_WAIT_L(0); PG8_BAR; PG8_MMA(1, 0, At, B0); PG8_MMA(1, 1, At, B1); PG8_BAR; PG8_SCHED;
.Lffout_noz:
	s_waitcnt vmcnt(8)
	s_waitcnt lgkmcnt(0)
	s_barrier
	s_setprio 1
	v_mfma_f32_16x16x32_bf16 v[142:145], v[114:117], v[180:183], v[142:145]
	v_mfma_f32_16x16x32_bf16 v[138:141], v[122:125], v[180:183], v[138:141]
	v_mfma_f32_16x16x32_bf16 v[110:113], v[114:117], v[192:195], v[110:113]
	v_mfma_f32_16x16x32_bf16 v[106:109], v[122:125], v[192:195], v[106:109]
	v_mfma_f32_16x16x32_bf16 v[94:97], v[114:117], v[200:203], v[94:97]
	v_mfma_f32_16x16x32_bf16 v[90:93], v[122:125], v[200:203], v[90:93]
	v_mfma_f32_16x16x32_bf16 v[78:81], v[114:117], v[208:211], v[78:81]
	v_mfma_f32_16x16x32_bf16 v[74:77], v[122:125], v[208:211], v[74:77]
	v_mfma_f32_16x16x32_bf16 v[142:145], v[118:121], v[188:191], v[142:145]
	v_mfma_f32_16x16x32_bf16 v[138:141], v[134:137], v[188:191], v[138:141]
	v_mfma_f32_16x16x32_bf16 v[110:113], v[118:121], v[196:199], v[110:113]
	v_mfma_f32_16x16x32_bf16 v[106:109], v[134:137], v[196:199], v[106:109]
	v_mfma_f32_16x16x32_bf16 v[94:97], v[118:121], v[204:207], v[94:97]
	v_mfma_f32_16x16x32_bf16 v[90:93], v[134:137], v[204:207], v[90:93]
	v_mfma_f32_16x16x32_bf16 v[78:81], v[118:121], v[212:215], v[78:81]
	v_mfma_f32_16x16x32_bf16 v[74:77], v[134:137], v[212:215], v[74:77]
	v_mfma_f32_16x16x32_bf16 v[130:133], v[146:149], v[180:183], v[130:133]
	v_mfma_f32_16x16x32_bf16 v[126:129], v[166:169], v[180:183], v[126:129]
	v_mfma_f32_16x16x32_bf16 v[102:105], v[146:149], v[192:195], v[102:105]
	v_mfma_f32_16x16x32_bf16 v[98:101], v[166:169], v[192:195], v[98:101]
	v_mfma_f32_16x16x32_bf16 v[86:89], v[146:149], v[200:203], v[86:89]
	v_mfma_f32_16x16x32_bf16 v[82:85], v[166:169], v[200:203], v[82:85]
	v_mfma_f32_16x16x32_bf16 v[70:73], v[146:149], v[208:211], v[70:73]
	v_mfma_f32_16x16x32_bf16 v[66:69], v[166:169], v[208:211], v[66:69]
	v_mfma_f32_16x16x32_bf16 v[130:133], v[150:153], v[188:191], v[130:133]
	v_mfma_f32_16x16x32_bf16 v[126:129], v[170:173], v[188:191], v[126:129]
	v_mfma_f32_16x16x32_bf16 v[102:105], v[150:153], v[196:199], v[102:105]
	v_mfma_f32_16x16x32_bf16 v[98:101], v[170:173], v[196:199], v[98:101]
	v_mfma_f32_16x16x32_bf16 v[86:89], v[150:153], v[204:207], v[86:89]
	v_mfma_f32_16x16x32_bf16 v[82:85], v[170:173], v[204:207], v[82:85]
	v_mfma_f32_16x16x32_bf16 v[70:73], v[150:153], v[212:215], v[70:73]
	v_mfma_f32_16x16x32_bf16 v[66:69], v[170:173], v[212:215], v[66:69]
	s_setprio 0
	s_barrier
	s_add_i32 s22, s51, s34
	v_lshl_add_u64 v[216:217], s[24:25], 0, v[158:159]
	s_mov_b32 m0, s22
	ds_read_b128 v[180:183], v186 offset:16384
	ds_read_b128 v[188:191], v186 offset:17408
	ds_read_b128 v[192:195], v186 offset:18432
	ds_read_b128 v[196:199], v186 offset:19456
	ds_read_b128 v[200:203], v186 offset:20480
	ds_read_b128 v[204:207], v186 offset:21504
	ds_read_b128 v[208:211], v186 offset:22528
	ds_read_b128 v[212:215], v186 offset:23552
	global_load_lds_dwordx4 v[216:217], off
	s_add_i32 m0, s22, 0x2000
	s_add_u32 s22, s24, 0xb0000
	v_lshl_add_u64 v[218:219], s[24:25], 0, v[154:155]
	s_addc_u32 s23, s25, 0
	s_add_i32 s51, s52, s34
	global_load_lds_dwordx4 v[218:219], off
	v_lshl_add_u64 v[220:221], s[22:23], 0, v[158:159]
	s_mov_b32 m0, s51
	v_lshl_add_u64 v[222:223], s[26:27], 0, v[156:157]
	global_load_lds_dwordx4 v[220:221], off
	v_lshl_add_u64 v[220:221], s[22:23], 0, v[154:155]
	s_add_i32 m0, s51, 0x2000
	s_nop 0
	global_load_lds_dwordx4 v[220:221], off
	v_lshl_add_u64 v[220:221], s[26:27], 0, v[160:161]
	s_mov_b32 m0, s35
	s_nop 0
	global_load_lds_dwordx4 v[220:221], off
	s_mov_b32 m0, s36
	s_nop 0
	global_load_lds_dwordx4 v[222:223], off
	s_waitcnt vmcnt(8)
	s_waitcnt lgkmcnt(0)
	s_barrier
	s_setprio 1
	v_mfma_f32_16x16x32_bf16 v[62:65], v[114:117], v[180:183], v[62:65]
	v_mfma_f32_16x16x32_bf16 v[58:61], v[122:125], v[180:183], v[58:61]
	v_mfma_f32_16x16x32_bf16 v[46:49], v[114:117], v[192:195], v[46:49]
	v_mfma_f32_16x16x32_bf16 v[42:45], v[122:125], v[192:195], v[42:45]
	v_mfma_f32_16x16x32_bf16 v[30:33], v[114:117], v[200:203], v[30:33]
	v_mfma_f32_16x16x32_bf16 v[26:29], v[122:125], v[200:203], v[26:29]
	v_mfma_f32_16x16x32_bf16 v[14:17], v[114:117], v[208:211], v[14:17]
	v_mfma_f32_16x16x32_bf16 v[10:13], v[122:125], v[208:211], v[10:13]
	v_mfma_f32_16x16x32_bf16 v[62:65], v[118:121], v[188:191], v[62:65]
	v_mfma_f32_16x16x32_bf16 v[58:61], v[134:137], v[188:191], v[58:61]
	v_mfma_f32_16x16x32_bf16 v[46:49], v[118:121], v[196:199], v[46:49]
	v_mfma_f32_16x16x32_bf16 v[42:45], v[134:137], v[196:199], v[42:45]
	v_mfma_f32_16x16x32_bf16 v[30:33], v[118:121], v[204:207], v[30:33]
	v_mfma_f32_16x16x32_bf16 v[26:29], v[134:137], v[204:207], v[26:29]
	v_mfma_f32_16x16x32_bf16 v[14:17], v[118:121], v[212:215], v[14:17]
	v_mfma_f32_16x16x32_bf16 v[10:13], v[134:137], v[212:215], v[10:13]
	v_mfma_f32_16x16x32_bf16 v[54:57], v[146:149], v[180:183], v[54:57]
	v_mfma_f32_16x16x32_bf16 v[50:53], v[166:169], v[180:183], v[50:53]
	v_mfma_f32_16x16x32_bf16 v[38:41], v[146:149], v[192:195], v[38:41]
	v_mfma_f32_16x16x32_bf16 v[34:37], v[166:169], v[192:195], v[34:37]
	v_mfma_f32_16x16x32_bf16 v[22:25], v[146:149], v[200:203], v[22:25]
	v_mfma_f32_16x16x32_bf16 v[18:21], v[166:169], v[200:203], v[18:21]
	v_mfma_f32_16x16x32_bf16 v[6:9], v[146:149], v[208:211], v[6:9]
	v_mfma_f32_16x16x32_bf16 v[2:5], v[166:169], v[208:211], v[2:5]
	v_mfma_f32_16x16x32_bf16 v[54:57], v[150:153], v[188:191], v[54:57]
	v_mfma_f32_16x16x32_bf16 v[50:53], v[170:173], v[188:191], v[50:53]
	v_mfma_f32_16x16x32_bf16 v[38:41], v[150:153], v[196:199], v[38:41]
	v_mfma_f32_16x16x32_bf16 v[34:37], v[170:173], v[196:199], v[34:37]
	v_mfma_f32_16x16x32_bf16 v[22:25], v[150:153], v[204:207], v[22:25]
	v_mfma_f32_16x16x32_bf16 v[18:21], v[170:173], v[204:207], v[18:21]
	v_mfma_f32_16x16x32_bf16 v[6:9], v[150:153], v[212:215], v[6:9]
	v_mfma_f32_16x16x32_bf16 v[2:5], v[170:173], v[212:215], v[2:5]
	s_setprio 0
	s_barrier
; #define PG8_STAGE(bufoff, gbase, voff) do { _Pragma("unroll") for (int _i = 0; _i < 2; ++_i) \
;         __builtin_amdgcn_global_load_lds((const unsigned*)((const char*)(gbase) + (voff)[_i]), (PG8_LAS unsigned*)(lds + (bufoff) + ldsw + _i * 8192), 16, 0, 0); } while (0)
; #define PG8_LDA(dst, b, h) do { _Pragma("unroll") for (int m = 0; m < 4; ++m) _Pragma("unroll") for (int k = 0; k < 2; ++k) dst[m][k] = *(const PG8_LAS bf16x8*)(lds + PG8_SA(b, h) + aoff + m * 2048 + k * 1024); } while (0)
; #define PG8_LDB(dst, b, h) do { _Pragma("unroll") for (int n = 0; n < 2; ++n) _Pragma("unroll") for (int k = 0; k < 2; ++k) dst[n][k] = *(const PG8_LAS bf16x8*)(lds + PG8_SB(b, h) + boff + n * 2048 + k * 1024); } while (0)
; #define PG8_MMA(ai, bj, At, Bt) do { __builtin_amdgcn_s_setprio(1); _Pragma("unroll") for (int m = 0; m < 4; ++m) _Pragma("unroll") for (int n = 0; n < 2; ++n) _Pragma("unroll") for (int k = 0; k < 2; ++k) \
;         acc[ai][bj][m][n] = __builtin_amdgcn_mfma_f32_16x16x32_bf16(Bt[n][k], At[m][k], acc[ai][bj][m][n], 0, 0, 0); __builtin_amdgcn_s_setprio(0); } while (0)
; #define PG8_WAIT_V(n) asm volatile("s_waitcnt vmcnt(" #n ")" ::: "memory")
; #define PG8_WAIT_L(n) asm volatile("s_waitcnt lgkmcnt(" #n ")" ::: "memory")
; #define PG8_BAR __builtin_amdgcn_s_barrier()
; #define PG8_SCHED __builtin_amdgcn_sched_barrier(0)
; template <class Epi, class Sched, bool ALIGN_EPI = false, bool SP2 = false>
; __device__ __forceinline__ void gemm_phase(PG8_LAS unsigned char* lds, const Gemm g, const Sched& S, const Epi& E) {
;     ...
;             PG8_LDB(B0, 1, 0); PG8_LDB(B1, 1, 1); PG8_SCHED; PG8_LDA(At, 1, 0); PG8_STAGE(PG8_SA(0, 1), a2 + hstep, voffA);
;             PG8_WAIT_V(8); PG8_WAIT_L(0); PG8_BAR; PG8_MMA(0, 0, At, B0); PG8_MMA(0, 1, At, B1); PG8_BAR; PG8_SCHED;
	s_add_i32 s51, 0, 0x18000
	s_add_i32 s52, 0, 0x1c000
	v_add_u32_e32 v134, s51, v185
	v_add_u32_e32 v170, s52, v185
	ds_read_b128 v[114:117], v134
	ds_read_b128 v[118:121], v134 offset:1024
	ds_read_b128 v[122:125], v134 offset:2048
	ds_read_b128 v[134:137], v134 offset:3072
	ds_read_b128 v[146:149], v170
	ds_read_b128 v[150:153], v170 offset:1024
	ds_read_b128 v[166:169], v170 offset:2048
	ds_read_b128 v[170:173], v170 offset:3072
	s_add_u32 s22, s26, 0xb0000
	s_addc_u32 s23, s27, 0
	s_mov_b32 m0, s37
	v_lshl_add_u64 v[228:229], s[22:23], 0, v[160:161]
	ds_read_b128 v[180:183], v186 offset:32768
	ds_read_b128 v[188:191], v186 offset:33792
	ds_read_b128 v[192:195], v186 offset:34816
	ds_read_b128 v[196:199], v186 offset:35840
	ds_read_b128 v[200:203], v186 offset:36864
	ds_read_b128 v[204:207], v186 offset:37888
	ds_read_b128 v[208:211], v186 offset:38912
	ds_read_b128 v[212:215], v186 offset:39936
	global_load_lds_dwordx4 v[228:229], off
	v_lshl_add_u64 v[228:229], s[22:23], 0, v[156:157]
	s_mov_b32 m0, s38
	s_nop 0
	global_load_lds_dwordx4 v[228:229], off
	s_waitcnt vmcnt(8)
	s_waitcnt lgkmcnt(0)
	s_barrier
	s_setprio 1
	v_mfma_f32_16x16x32_bf16 v[142:145], v[114:117], v[180:183], v[142:145]
	v_mfma_f32_16x16x32_bf16 v[138:141], v[122:125], v[180:183], v[138:141]
	v_mfma_f32_16x16x32_bf16 v[110:113], v[114:117], v[192:195], v[110:113]
	v_mfma_f32_16x16x32_bf16 v[106:109], v[122:125], v[192:195], v[106:109]
	v_mfma_f32_16x16x32_bf16 v[94:97], v[114:117], v[200:203], v[94:97]
	v_mfma_f32_16x16x32_bf16 v[90:93], v[122:125], v[200:203], v[90:93]
	v_mfma_f32_16x16x32_bf16 v[78:81], v[114:117], v[208:211], v[78:81]
	v_mfma_f32_16x16x32_bf16 v[74:77], v[122:125], v[208:211], v[74:77]
	v_mfma_f32_16x16x32_bf16 v[142:145], v[118:121], v[188:191], v[142:145]
	v_mfma_f32_16x16x32_bf16 v[138:141], v[134:137], v[188:191], v[138:141]
	v_mfma_f32_16x16x32_bf16 v[110:113], v[118:121], v[196:199], v[110:113]
	v_mfma_f32_16x16x32_bf16 v[106:109], v[134:137], v[196:199], v[106:109]
	v_mfma_f32_16x16x32_bf16 v[94:97], v[118:121], v[204:207], v[94:97]
	v_mfma_f32_16x16x32_bf16 v[90:93], v[134:137], v[204:207], v[90:93]
	v_mfma_f32_16x16x32_bf16 v[78:81], v[118:121], v[212:215], v[78:81]
	v_mfma_f32_16x16x32_bf16 v[74:77], v[134:137], v[212:215], v[74:77]
	v_mfma_f32_16x16x32_bf16 v[130:133], v[146:149], v[180:183], v[130:133]
	v_mfma_f32_16x16x32_bf16 v[126:129], v[166:169], v[180:183], v[126:129]
	v_mfma_f32_16x16x32_bf16 v[102:105], v[146:149], v[192:195], v[102:105]
	v_mfma_f32_16x16x32_bf16 v[98:101], v[166:169], v[192:195], v[98:101]
	v_mfma_f32_16x16x32_bf16 v[86:89], v[146:149], v[200:203], v[86:89]
	v_mfma_f32_16x16x32_bf16 v[82:85], v[166:169], v[200:203], v[82:85]
	v_mfma_f32_16x16x32_bf16 v[70:73], v[146:149], v[208:211], v[70:73]
	v_mfma_f32_16x16x32_bf16 v[66:69], v[166:169], v[208:211], v[66:69]
	v_mfma_f32_16x16x32_bf16 v[130:133], v[150:153], v[188:191], v[130:133]
	v_mfma_f32_16x16x32_bf16 v[126:129], v[170:173], v[188:191], v[126:129]
	v_mfma_f32_16x16x32_bf16 v[102:105], v[150:153], v[196:199], v[102:105]
	v_mfma_f32_16x16x32_bf16 v[98:101], v[170:173], v[196:199], v[98:101]
	v_mfma_f32_16x16x32_bf16 v[86:89], v[150:153], v[204:207], v[86:89]
	v_mfma_f32_16x16x32_bf16 v[82:85], v[170:173], v[204:207], v[82:85]
	v_mfma_f32_16x16x32_bf16 v[70:73], v[150:153], v[212:215], v[70:73]
	v_mfma_f32_16x16x32_bf16 v[66:69], v[170:173], v[212:215], v[66:69]
	s_setprio 0
	s_barrier
; #define PG8_STAGE(bufoff, gbase, voff) do { _Pragma("unroll") for (int _i = 0; _i < 2; ++_i) \
;         __builtin_amdgcn_global_load_lds((const unsigned*)((const char*)(gbase) + (voff)[_i]), (PG8_LAS unsigned*)(lds + (bufoff) + ldsw + _i * 8192), 16, 0, 0); } while (0)
; #define PG8_LDA(dst, b, h) do { _Pragma("unroll") for (int m = 0; m < 4; ++m) _Pragma("unroll") for (int k = 0; k < 2; ++k) dst[m][k] = *(const PG8_LAS bf16x8*)(lds + PG8_SA(b, h) + aoff + m * 2048 + k * 1024); } while (0)
; #define PG8_MMA(ai, bj, At, Bt) do { __builtin_amdgcn_s_setprio(1); _Pragma("unroll") for (int m = 0; m < 4; ++m) _Pragma("unroll") for (int n = 0; n < 2; ++n) _Pragma("unroll") for (int k = 0; k < 2; ++k) \
;         acc[ai][bj][m][n] = __builtin_amdgcn_mfma_f32_16x16x32_bf16(Bt[n][k], At[m][k], acc[ai][bj][m][n], 0, 0, 0); __builtin_amdgcn_s_setprio(0); } while (0)
; #define PG8_WAIT_V(n) asm volatile("s_waitcnt vmcnt(" #n ")" ::: "memory")
; #define PG8_WAIT_L(n) asm volatile("s_waitcnt lgkmcnt(" #n ")" ::: "memory")
; #define PG8_BAR __builtin_amdgcn_s_barrier()
; #define PG8_SCHED __builtin_amdgcn_sched_barrier(0)
; template <class Epi, class Sched, bool ALIGN_EPI = false, bool SP2 = false>
; __device__ __forceinline__ void gemm_phase(PG8_LAS unsigned char* lds, const Gemm g, const Sched& S, const Epi& E) {
;     ...
;         for (int t = 0; t < nt; t += 2) {
;             const bool last = (t == nt - 2);
;             const char* a1 = cA + (size_t)(t + 1) * kstep;
;             const char* a2 = last ? nA : cA + (size_t)(t + 2) * kstep; const char* b2 = last ? nB : cB + (size_t)(t + 2) * kstep;
;             const char* a3 = a2 + kstep; const char* b3 = b2 + kstep;
;     ...
;             PG8_LDA(At, 1, 1); PG8_STAGE(PG8_SB(1, 0), b3, voffB); PG8_STAGE(PG8_SB(1, 1), b3 + hstep, voffB); PG8_STAGE(PG8_SA(1, 0), a3, voffA);
;             PG8_WAIT_V(8); PG8_WAIT_L(0); PG8_BAR; PG8_MMA(1, 0, At, B0); PG8_MMA(1, 1, At, B1); PG8_BAR; PG8_SCHED;
	s_add_i32 s22, s51, s34
	v_lshl_add_u64 v[216:217], v[216:217], 0, s[96:97]
	s_mov_b32 m0, s22
	ds_read_b128 v[180:183], v186 offset:49152
	ds_read_b128 v[188:191], v186 offset:50176
	ds_read_b128 v[192:195], v186 offset:51200
	ds_read_b128 v[196:199], v186 offset:52224
	ds_read_b128 v[200:203], v186 offset:53248
	ds_read_b128 v[204:207], v186 offset:54272
	ds_read_b128 v[208:211], v186 offset:55296
	ds_read_b128 v[212:215], v186 offset:56320
	global_load_lds_dwordx4 v[216:217], off
	s_add_i32 m0, s22, 0x2000
	s_add_u32 s22, s24, 0xb0080
	v_lshl_add_u64 v[216:217], v[218:219], 0, s[96:97]
	s_addc_u32 s23, s25, 0
	s_add_i32 s24, s52, s34
	global_load_lds_dwordx4 v[216:217], off
	v_lshl_add_u64 v[216:217], s[22:23], 0, v[158:159]
	s_mov_b32 m0, s24
	s_nop 0
	global_load_lds_dwordx4 v[216:217], off
	v_lshl_add_u64 v[216:217], s[22:23], 0, v[154:155]
	s_add_i32 m0, s24, 0x2000
	s_nop 0
	global_load_lds_dwordx4 v[216:217], off
	v_lshl_add_u64 v[216:217], v[220:221], 0, s[96:97]
	s_mov_b32 m0, s41
	s_nop 0
	global_load_lds_dwordx4 v[216:217], off
	v_lshl_add_u64 v[216:217], v[222:223], 0, s[96:97]
	s_mov_b32 m0, s42
	s_nop 0
	global_load_lds_dwordx4 v[216:217], off
	s_waitcnt vmcnt(8)
	s_waitcnt lgkmcnt(0)
	s_barrier
	s_setprio 1
	v_mfma_f32_16x16x32_bf16 v[62:65], v[114:117], v[180:183], v[62:65]
	v_mfma_f32_16x16x32_bf16 v[58:61], v[122:125], v[180:183], v[58:61]
	v_mfma_f32_16x16x32_bf16 v[46:49], v[114:117], v[192:195], v[46:49]
	v_mfma_f32_16x16x32_bf16 v[42:45], v[122:125], v[192:195], v[42:45]
	v_mfma_f32_16x16x32_bf16 v[30:33], v[114:117], v[200:203], v[30:33]
	v_mfma_f32_16x16x32_bf16 v[26:29], v[122:125], v[200:203], v[26:29]
	v_mfma_f32_16x16x32_bf16 v[14:17], v[114:117], v[208:211], v[14:17]
	v_mfma_f32_16x16x32_bf16 v[10:13], v[122:125], v[208:211], v[10:13]
	v_mfma_f32_16x16x32_bf16 v[62:65], v[118:121], v[188:191], v[62:65]
	v_mfma_f32_16x16x32_bf16 v[58:61], v[134:137], v[188:191], v[58:61]
	v_mfma_f32_16x16x32_bf16 v[46:49], v[118:121], v[196:199], v[46:49]
	v_mfma_f32_16x16x32_bf16 v[42:45], v[134:137], v[196:199], v[42:45]
	v_mfma_f32_16x16x32_bf16 v[30:33], v[118:121], v[204:207], v[30:33]
	v_mfma_f32_16x16x32_bf16 v[26:29], v[134:137], v[204:207], v[26:29]
	v_mfma_f32_16x16x32_bf16 v[14:17], v[118:121], v[212:215], v[14:17]
	v_mfma_f32_16x16x32_bf16 v[10:13], v[134:137], v[212:215], v[10:13]
	v_mfma_f32_16x16x32_bf16 v[54:57], v[146:149], v[180:183], v[54:57]
	v_mfma_f32_16x16x32_bf16 v[50:53], v[166:169], v[180:183], v[50:53]
	v_mfma_f32_16x16x32_bf16 v[38:41], v[146:149], v[192:195], v[38:41]
	v_mfma_f32_16x16x32_bf16 v[34:37], v[166:169], v[192:195], v[34:37]
	v_mfma_f32_16x16x32_bf16 v[22:25], v[146:149], v[200:203], v[22:25]
	v_mfma_f32_16x16x32_bf16 v[18:21], v[166:169], v[200:203], v[18:21]
	v_mfma_f32_16x16x32_bf16 v[6:9], v[146:149], v[208:211], v[6:9]
	v_mfma_f32_16x16x32_bf16 v[2:5], v[166:169], v[208:211], v[2:5]
	v_mfma_f32_16x16x32_bf16 v[54:57], v[150:153], v[188:191], v[54:57]
	v_mfma_f32_16x16x32_bf16 v[50:53], v[170:173], v[188:191], v[50:53]
	v_mfma_f32_16x16x32_bf16 v[38:41], v[150:153], v[196:199], v[38:41]
	v_mfma_f32_16x16x32_bf16 v[34:37], v[170:173], v[196:199], v[34:37]
	v_mfma_f32_16x16x32_bf16 v[22:25], v[150:153], v[204:207], v[22:25]
	v_mfma_f32_16x16x32_bf16 v[18:21], v[170:173], v[204:207], v[18:21]
	v_mfma_f32_16x16x32_bf16 v[6:9], v[150:153], v[212:215], v[6:9]
	v_mfma_f32_16x16x32_bf16 v[2:5], v[170:173], v[212:215], v[2:5]
	s_setprio 0
	s_barrier
	s_add_i32 s50, s50, 2
	s_add_u32 s33, s33, 0x100
	s_addc_u32 s49, s49, 0
	s_cmp_gt_u32 s50, 41
	s_mov_b64 s[22:23], s[8:9]
	s_cbranch_scc0 .LBB0_1360
	s_and_b64 vcc, exec, s[14:15]
	s_cbranch_vccz .LBB0_1363
	s_barrier
